# NA PV step: ds_read2_b64 split into two ds_read_b64 (64-bank addressing removes the 2-way conflict between V^T rows fr and fr+8); lgkmcnt counts doubled
# speedup vs baseline: 1.0053x; 1.0053x over previous
; __device__ __forceinline__ void na2_task(const Params& p_, int l, int task, unsigned char* lds) {
;     ...
;     { const int pair = lane & 31, chunk = (lane >> 5) + 2 * (w & 3);
;       unsigned* VTd = (unsigned*)(VT + (size_t)hh * 64 * 520);
;       u32x4 xs[8], ys[8];
; #pragma unroll
;       for (int a = 0; a < 8; ++a) { const size_t tok = (size_t)b * SEQ + (row_start + a) * 64 + 2 * pair;
;           const bf16* src = Z + tok * DIN + 4 * DG + h * 64 + chunk * 8; xs[a] = *(const u32x4*)src; ys[a] = *(const u32x4*)(src + DIN); }
;     ...
;             for (int i = 0; i < 8; ++i) { const int a = 4 + i / 2, ci = i % 2;
;                 const size_t ktok = (size_t)b * SEQ + (row_start + a) * 64 + kst + 16 * ci + fr;
; #pragma unroll
;                 for (int ks = 0; ks < 2; ++ks) kfr[i][ks] = *(const bf16x8v*)(Z + ktok * DIN + 3 * DG + h * 64 + 32 * ks + 8 * fq); }
.LBB0_385:
	v_bfe_u32 v172, v147, 2, 3
	v_bfe_u32 v249, v147, 6, 2
	v_lshl_or_b32 v172, v249, 3, v172
	v_lshl_or_b32 v88, v172, 1, s42
	v_or_b32_e32 v81, s24, v88
	v_mov_b64_e32 v[86:87], s[40:41]
	v_and_b32_e32 v173, 3, v147
	v_bfe_u32 v249, v147, 5, 1
	v_lshl_or_b32 v173, v249, 2, v173
	v_lshlrev_b32_e32 v173, 3, v173
	v_mad_u64_u32 v[94:95], s[40:41], v81, s75, v[86:87]
	v_mad_i32_i24 v95, s43, v195, v95
	v_mov_b32_e32 v89, s43
	v_lshl_add_u64 v[94:95], v[94:95], 0, v[76:77]
	v_lshlrev_b32_e32 v164, 1, v173
	v_mov_b32_e32 v165, v1
	v_lshl_add_u64 v[94:95], v[94:95], 0, v[164:165]
	v_lshl_add_u64 v[102:103], v[88:89], 0, s[44:45]
	v_add_co_u32_e32 v96, vcc, s74, v94
	v_mad_u64_u32 v[104:105], s[40:41], v102, s75, v[86:87]
	s_nop 0
	v_addc_co_u32_e32 v97, vcc, 0, v95, vcc
	v_mad_i32_i24 v105, v103, s75, v105
	v_add_co_u32_e32 v98, vcc, s7, v94
	v_lshl_add_u64 v[102:103], v[104:105], 0, v[76:77]
	s_nop 0
	v_addc_co_u32_e32 v99, vcc, 0, v95, vcc
	v_lshl_add_u64 v[102:103], v[102:103], 0, v[164:165]
	global_load_dwordx4 v[94:97], v[96:97], off
	s_nop 0
	global_load_dwordx4 v[98:101], v[98:99], off offset:1024
	v_add_co_u32_e32 v104, vcc, s74, v102
	v_lshl_add_u64 v[110:111], v[88:89], 0, s[46:47]
	s_nop 0
	v_addc_co_u32_e32 v105, vcc, 0, v103, vcc
	v_add_co_u32_e32 v106, vcc, s7, v102
	v_mad_u64_u32 v[112:113], s[40:41], v110, s75, v[86:87]
	s_nop 0
	v_addc_co_u32_e32 v107, vcc, 0, v103, vcc
	global_load_dwordx4 v[102:105], v[104:105], off
	s_nop 0
	global_load_dwordx4 v[106:109], v[106:107], off offset:1024
	v_mad_i32_i24 v113, v111, s75, v113
	v_lshl_add_u64 v[110:111], v[112:113], 0, v[76:77]
	v_lshl_add_u64 v[110:111], v[110:111], 0, v[164:165]
	v_lshl_add_u64 v[118:119], v[88:89], 0, s[48:49]
	v_add_co_u32_e32 v112, vcc, s74, v110
	v_mad_u64_u32 v[120:121], s[40:41], v118, s75, v[86:87]
	s_nop 0
	v_addc_co_u32_e32 v113, vcc, 0, v111, vcc
	v_mad_i32_i24 v121, v119, s75, v121
	v_add_co_u32_e32 v114, vcc, s7, v110
	v_lshl_add_u64 v[118:119], v[120:121], 0, v[76:77]
	s_nop 0
	v_addc_co_u32_e32 v115, vcc, 0, v111, vcc
	v_lshl_add_u64 v[118:119], v[118:119], 0, v[164:165]
	v_add_co_u32_e32 v120, vcc, s74, v118
	global_load_dwordx4 v[110:113], v[112:113], off
	s_nop 0
	global_load_dwordx4 v[114:117], v[114:115], off offset:1024
	v_addc_co_u32_e32 v121, vcc, 0, v119, vcc
	v_add_co_u32_e32 v122, vcc, s7, v118
	s_add_i32 s44, s24, 0x100
	s_nop 0
	v_addc_co_u32_e32 v123, vcc, 0, v119, vcc
	global_load_dwordx4 v[118:121], v[120:121], off
	s_nop 0
	global_load_dwordx4 v[122:125], v[122:123], off offset:1024
	s_mov_b32 s45, s25
	v_lshl_add_u64 v[126:127], v[88:89], 0, s[44:45]
	v_mad_u64_u32 v[128:129], s[40:41], v126, s75, v[86:87]
	v_mad_i32_i24 v129, v127, s75, v129
	v_lshl_add_u64 v[126:127], v[128:129], 0, v[76:77]
	s_add_i32 s42, s24, 0x140
	s_mov_b32 s43, s25
	v_lshl_add_u64 v[126:127], v[126:127], 0, v[164:165]
	v_lshl_add_u64 v[134:135], v[88:89], 0, s[42:43]
	v_add_co_u32_e32 v128, vcc, s74, v126
	v_mad_u64_u32 v[136:137], s[40:41], v134, s75, v[86:87]
	s_nop 0
	v_addc_co_u32_e32 v129, vcc, 0, v127, vcc
	v_mad_i32_i24 v137, v135, s75, v137
	v_add_co_u32_e32 v130, vcc, s7, v126
	v_lshl_add_u64 v[134:135], v[136:137], 0, v[76:77]
	s_nop 0
	v_addc_co_u32_e32 v131, vcc, 0, v127, vcc
	v_lshl_add_u64 v[134:135], v[134:135], 0, v[164:165]
	v_add_co_u32_e32 v136, vcc, s74, v134
	global_load_dwordx4 v[126:129], v[128:129], off
	s_nop 0
	global_load_dwordx4 v[130:133], v[130:131], off offset:1024
	v_addc_co_u32_e32 v137, vcc, 0, v135, vcc
	v_add_co_u32_e32 v138, vcc, s7, v134
	s_add_i32 s40, s24, 0x180
	s_nop 0
	v_addc_co_u32_e32 v139, vcc, 0, v135, vcc
	global_load_dwordx4 v[134:137], v[136:137], off
	s_nop 0
	global_load_dwordx4 v[138:141], v[138:139], off offset:1024
	s_mov_b32 s41, s25
	v_lshl_add_u64 v[142:143], v[88:89], 0, s[40:41]
	v_mad_u64_u32 v[144:145], s[46:47], v142, s75, v[86:87]
	v_mad_i32_i24 v145, v143, s75, v145
	v_lshl_add_u64 v[142:143], v[144:145], 0, v[76:77]
	s_addk_i32 s24, 0x1c0
	v_lshl_add_u64 v[142:143], v[142:143], 0, v[164:165]
	v_lshl_add_u64 v[88:89], v[88:89], 0, s[24:25]
	v_add_co_u32_e32 v144, vcc, s74, v142
	v_mad_u64_u32 v[166:167], s[46:47], v88, s75, v[86:87]
	s_nop 0
	v_addc_co_u32_e32 v145, vcc, 0, v143, vcc
	v_mad_i32_i24 v167, v89, s75, v167
	v_add_co_u32_e32 v160, vcc, s7, v142
	v_lshl_add_u64 v[88:89], v[166:167], 0, v[76:77]
	s_nop 0
	v_addc_co_u32_e32 v161, vcc, 0, v143, vcc
	v_lshl_add_u64 v[88:89], v[88:89], 0, v[164:165]
	v_add_co_u32_e32 v164, vcc, s74, v88
	global_load_dwordx4 v[142:145], v[144:145], off
	s_nop 0
	global_load_dwordx4 v[160:163], v[160:161], off offset:1024
	v_addc_co_u32_e32 v165, vcc, 0, v89, vcc
	v_add_co_u32_e32 v88, vcc, s7, v88
	s_mov_b32 s13, 0x10400
	s_nop 0
	v_addc_co_u32_e32 v89, vcc, 0, v89, vcc
	global_load_dwordx4 v[164:167], v[164:165], off
	s_nop 0
	global_load_dwordx4 v[168:171], v[88:89], off offset:1024
	v_add_u32_e32 v208, s44, v82
	v_mad_u64_u32 v[206:207], s[98:99], v208, s75, v[86:87]
	v_lshl_add_u64 v[206:207], v[206:207], 0, v[76:77]
	v_lshl_add_u64 v[206:207], v[206:207], 0, v[252:253]
	global_load_dwordx4 v[210:213], v[206:207], off offset:3072
	global_load_dwordx4 v[214:217], v[206:207], off offset:3136
	v_add_u32_e32 v208, s44, v84
	v_mad_u64_u32 v[206:207], s[98:99], v208, s75, v[86:87]
	v_lshl_add_u64 v[206:207], v[206:207], 0, v[76:77]
	v_lshl_add_u64 v[206:207], v[206:207], 0, v[252:253]
	global_load_dwordx4 v[218:221], v[206:207], off offset:3072
	global_load_dwordx4 v[222:225], v[206:207], off offset:3136
	v_add_u32_e32 v208, s42, v82
	v_mad_u64_u32 v[206:207], s[98:99], v208, s75, v[86:87]
	v_lshl_add_u64 v[206:207], v[206:207], 0, v[76:77]
	v_lshl_add_u64 v[206:207], v[206:207], 0, v[252:253]
	global_load_dwordx4 v[226:229], v[206:207], off offset:3072
	global_load_dwordx4 v[230:233], v[206:207], off offset:3136
	v_add_u32_e32 v208, s42, v84
	v_mad_u64_u32 v[206:207], s[98:99], v208, s75, v[86:87]
	v_lshl_add_u64 v[206:207], v[206:207], 0, v[76:77]
	v_lshl_add_u64 v[206:207], v[206:207], 0, v[252:253]
	global_load_dwordx4 v[234:237], v[206:207], off offset:3072
	s_waitcnt vmcnt(25)
; __device__ __forceinline__ void na2_task(const Params& p_, int l, int task, unsigned char* lds) {
;     ...
;     bf16x8v qf[2], kfr[8][2];
; #pragma unroll
;     for (int ks = 0; ks < 2; ++ks) qf[ks] = *(const bf16x8v*)(Z + qtok * DIN + 2 * DG + h * 64 + 32 * ks + 8 * fq);
; #pragma unroll
;     for (int i = 0; i < 8; ++i) { const int a = i / 2, ci = i % 2;
;         const size_t ktok = (size_t)b * SEQ + (row_start + a) * 64 + kst + 16 * ci + fr;
; #pragma unroll
;         for (int ks = 0; ks < 2; ++ks) kfr[i][ks] = *(const bf16x8v*)(Z + ktok * DIN + 3 * DG + h * 64 + 32 * ks + 8 * fq); }
;     ...
;       for (int a = 0; a < 8; ++a) { const unsigned xu[4] = {xs[a].x, xs[a].y, xs[a].z, xs[a].w}, yu[4] = {ys[a].x, ys[a].y, ys[a].z, ys[a].w};
; #pragma unroll
;           for (int i = 0; i < 4; ++i) { VTd[(chunk * 8 + 2 * i) * 260 + a * 32 + pair] = (xu[i] & 0xffffu) | (yu[i] << 16);
;               VTd[(chunk * 8 + 2 * i + 1) * 260 + a * 32 + pair] = (xu[i] >> 16) | (yu[i] & 0xffff0000u); } } }
	ds_bpermute_b32 v70, v251, v70
	ds_bpermute_b32 v71, v251, v71
	ds_bpermute_b32 v72, v251, v72
	ds_bpermute_b32 v73, v251, v73
	ds_bpermute_b32 v66, v251, v66
	ds_bpermute_b32 v67, v251, v67
	ds_bpermute_b32 v68, v251, v68
	ds_bpermute_b32 v69, v251, v69
	ds_bpermute_b32 v62, v251, v62
	ds_bpermute_b32 v63, v251, v63
	ds_bpermute_b32 v64, v251, v64
	ds_bpermute_b32 v65, v251, v65
	ds_bpermute_b32 v58, v251, v58
	ds_bpermute_b32 v59, v251, v59
	ds_bpermute_b32 v60, v251, v60
	ds_bpermute_b32 v61, v251, v61
	ds_bpermute_b32 v18, v251, v18
	ds_bpermute_b32 v19, v251, v19
	ds_bpermute_b32 v20, v251, v20
	ds_bpermute_b32 v21, v251, v21
	ds_bpermute_b32 v10, v251, v10
	ds_bpermute_b32 v11, v251, v11
	ds_bpermute_b32 v12, v251, v12
	ds_bpermute_b32 v13, v251, v13
	ds_bpermute_b32 v38, v251, v38
	ds_bpermute_b32 v39, v251, v39
	ds_bpermute_b32 v40, v251, v40
	ds_bpermute_b32 v41, v251, v41
	ds_bpermute_b32 v22, v251, v22
	ds_bpermute_b32 v23, v251, v23
	ds_bpermute_b32 v24, v251, v24
	ds_bpermute_b32 v25, v251, v25
	ds_bpermute_b32 v54, v251, v54
	ds_bpermute_b32 v55, v251, v55
	ds_bpermute_b32 v56, v251, v56
	ds_bpermute_b32 v57, v251, v57
	ds_bpermute_b32 v42, v251, v42
	ds_bpermute_b32 v43, v251, v43
	ds_bpermute_b32 v44, v251, v44
	ds_bpermute_b32 v45, v251, v45
	ds_bpermute_b32 v46, v251, v46
	ds_bpermute_b32 v47, v251, v47
	ds_bpermute_b32 v48, v251, v48
	ds_bpermute_b32 v49, v251, v49
	ds_bpermute_b32 v30, v251, v30
	ds_bpermute_b32 v31, v251, v31
	ds_bpermute_b32 v32, v251, v32
	ds_bpermute_b32 v33, v251, v33
	ds_bpermute_b32 v26, v251, v26
	ds_bpermute_b32 v27, v251, v27
	ds_bpermute_b32 v28, v251, v28
	ds_bpermute_b32 v29, v251, v29
	ds_bpermute_b32 v14, v251, v14
	ds_bpermute_b32 v15, v251, v15
	ds_bpermute_b32 v16, v251, v16
	ds_bpermute_b32 v17, v251, v17
	ds_bpermute_b32 v50, v251, v50
	ds_bpermute_b32 v51, v251, v51
	ds_bpermute_b32 v52, v251, v52
	ds_bpermute_b32 v53, v251, v53
	ds_bpermute_b32 v34, v251, v34
	ds_bpermute_b32 v35, v251, v35
	ds_bpermute_b32 v36, v251, v36
	ds_bpermute_b32 v37, v251, v37
	s_waitcnt vmcnt(7)
	v_and_b32_e32 v248, 1, v147
	v_cmp_eq_u32_e32 vcc, 1, v248
	v_and_b32_e32 v248, 2, v147
	v_cmp_eq_u32_e64 s[98:99], 2, v248
	s_nop 1
	v_cndmask_b32_e32 v246, v94, v95, vcc
	v_cndmask_b32_e32 v247, v95, v96, vcc
	v_cndmask_b32_e32 v248, v96, v97, vcc
	v_cndmask_b32_e32 v249, v97, v94, vcc
	v_cndmask_b32_e64 v94, v246, v248, s[98:99]
	v_cndmask_b32_e64 v95, v247, v249, s[98:99]
	v_cndmask_b32_e64 v96, v248, v246, s[98:99]
	v_cndmask_b32_e64 v97, v249, v247, s[98:99]
	v_cndmask_b32_e32 v246, v98, v99, vcc
	v_cndmask_b32_e32 v247, v99, v100, vcc
	v_cndmask_b32_e32 v248, v100, v101, vcc
	v_cndmask_b32_e32 v249, v101, v98, vcc
	v_cndmask_b32_e64 v98, v246, v248, s[98:99]
	v_cndmask_b32_e64 v99, v247, v249, s[98:99]
	v_cndmask_b32_e64 v100, v248, v246, s[98:99]
	v_cndmask_b32_e64 v101, v249, v247, s[98:99]
	v_cndmask_b32_e32 v246, v102, v103, vcc
	v_cndmask_b32_e32 v247, v103, v104, vcc
	v_cndmask_b32_e32 v248, v104, v105, vcc
	v_cndmask_b32_e32 v249, v105, v102, vcc
	v_cndmask_b32_e64 v102, v246, v248, s[98:99]
	v_cndmask_b32_e64 v103, v247, v249, s[98:99]
	v_cndmask_b32_e64 v104, v248, v246, s[98:99]
	v_cndmask_b32_e64 v105, v249, v247, s[98:99]
	v_cndmask_b32_e32 v246, v106, v107, vcc
	v_cndmask_b32_e32 v247, v107, v108, vcc
	v_cndmask_b32_e32 v248, v108, v109, vcc
	v_cndmask_b32_e32 v249, v109, v106, vcc
	v_cndmask_b32_e64 v106, v246, v248, s[98:99]
	v_cndmask_b32_e64 v107, v247, v249, s[98:99]
	v_cndmask_b32_e64 v108, v248, v246, s[98:99]
	v_cndmask_b32_e64 v109, v249, v247, s[98:99]
	v_cndmask_b32_e32 v246, v110, v111, vcc
	v_cndmask_b32_e32 v247, v111, v112, vcc
	v_cndmask_b32_e32 v248, v112, v113, vcc
	v_cndmask_b32_e32 v249, v113, v110, vcc
	v_cndmask_b32_e64 v110, v246, v248, s[98:99]
	v_cndmask_b32_e64 v111, v247, v249, s[98:99]
	v_cndmask_b32_e64 v112, v248, v246, s[98:99]
	v_cndmask_b32_e64 v113, v249, v247, s[98:99]
	v_cndmask_b32_e32 v246, v114, v115, vcc
	v_cndmask_b32_e32 v247, v115, v116, vcc
	v_cndmask_b32_e32 v248, v116, v117, vcc
	v_cndmask_b32_e32 v249, v117, v114, vcc
	v_cndmask_b32_e64 v114, v246, v248, s[98:99]
	v_cndmask_b32_e64 v115, v247, v249, s[98:99]
	v_cndmask_b32_e64 v116, v248, v246, s[98:99]
	v_cndmask_b32_e64 v117, v249, v247, s[98:99]
	v_cndmask_b32_e32 v246, v118, v119, vcc
	v_cndmask_b32_e32 v247, v119, v120, vcc
	v_cndmask_b32_e32 v248, v120, v121, vcc
	v_cndmask_b32_e32 v249, v121, v118, vcc
	v_cndmask_b32_e64 v118, v246, v248, s[98:99]
	v_cndmask_b32_e64 v119, v247, v249, s[98:99]
	v_cndmask_b32_e64 v120, v248, v246, s[98:99]
	v_cndmask_b32_e64 v121, v249, v247, s[98:99]
	v_cndmask_b32_e32 v246, v122, v123, vcc
	v_cndmask_b32_e32 v247, v123, v124, vcc
	v_cndmask_b32_e32 v248, v124, v125, vcc
	v_cndmask_b32_e32 v249, v125, v122, vcc
	v_cndmask_b32_e64 v122, v246, v248, s[98:99]
	v_cndmask_b32_e64 v123, v247, v249, s[98:99]
	v_cndmask_b32_e64 v124, v248, v246, s[98:99]
	v_cndmask_b32_e64 v125, v249, v247, s[98:99]
	v_cndmask_b32_e32 v246, v126, v127, vcc
	v_cndmask_b32_e32 v247, v127, v128, vcc
	v_cndmask_b32_e32 v248, v128, v129, vcc
	v_cndmask_b32_e32 v249, v129, v126, vcc
	v_cndmask_b32_e64 v126, v246, v248, s[98:99]
	v_cndmask_b32_e64 v127, v247, v249, s[98:99]
	v_cndmask_b32_e64 v128, v248, v246, s[98:99]
	v_cndmask_b32_e64 v129, v249, v247, s[98:99]
	v_cndmask_b32_e32 v246, v130, v131, vcc
	v_cndmask_b32_e32 v247, v131, v132, vcc
	v_cndmask_b32_e32 v248, v132, v133, vcc
	v_cndmask_b32_e32 v249, v133, v130, vcc
	v_cndmask_b32_e64 v130, v246, v248, s[98:99]
	v_cndmask_b32_e64 v131, v247, v249, s[98:99]
	v_cndmask_b32_e64 v132, v248, v246, s[98:99]
; __device__ __forceinline__ void na2_task(const Params& p_, int l, int task, unsigned char* lds) {
;     ...
;       for (int a = 0; a < 8; ++a) { const unsigned xu[4] = {xs[a].x, xs[a].y, xs[a].z, xs[a].w}, yu[4] = {ys[a].x, ys[a].y, ys[a].z, ys[a].w};
; #pragma unroll
;           for (int i = 0; i < 4; ++i) { VTd[(chunk * 8 + 2 * i) * 260 + a * 32 + pair] = (xu[i] & 0xffffu) | (yu[i] << 16);
;               VTd[(chunk * 8 + 2 * i + 1) * 260 + a * 32 + pair] = (xu[i] >> 16) | (yu[i] & 0xffff0000u); } } }
	v_cndmask_b32_e64 v133, v249, v247, s[98:99]
	v_cndmask_b32_e32 v246, v134, v135, vcc
	v_cndmask_b32_e32 v247, v135, v136, vcc
	v_cndmask_b32_e32 v248, v136, v137, vcc
	v_cndmask_b32_e32 v249, v137, v134, vcc
	v_cndmask_b32_e64 v134, v246, v248, s[98:99]
	v_cndmask_b32_e64 v135, v247, v249, s[98:99]
	v_cndmask_b32_e64 v136, v248, v246, s[98:99]
	v_cndmask_b32_e64 v137, v249, v247, s[98:99]
	v_cndmask_b32_e32 v246, v138, v139, vcc
	v_cndmask_b32_e32 v247, v139, v140, vcc
	v_cndmask_b32_e32 v248, v140, v141, vcc
	v_cndmask_b32_e32 v249, v141, v138, vcc
	v_cndmask_b32_e64 v138, v246, v248, s[98:99]
	v_cndmask_b32_e64 v139, v247, v249, s[98:99]
	v_cndmask_b32_e64 v140, v248, v246, s[98:99]
	v_cndmask_b32_e64 v141, v249, v247, s[98:99]
	v_cndmask_b32_e32 v246, v142, v143, vcc
	v_cndmask_b32_e32 v247, v143, v144, vcc
	v_cndmask_b32_e32 v248, v144, v145, vcc
	v_cndmask_b32_e32 v249, v145, v142, vcc
	v_cndmask_b32_e64 v142, v246, v248, s[98:99]
	v_cndmask_b32_e64 v143, v247, v249, s[98:99]
	v_cndmask_b32_e64 v144, v248, v246, s[98:99]
	v_cndmask_b32_e64 v145, v249, v247, s[98:99]
	v_cndmask_b32_e32 v246, v160, v161, vcc
	v_cndmask_b32_e32 v247, v161, v162, vcc
	v_cndmask_b32_e32 v248, v162, v163, vcc
	v_cndmask_b32_e32 v249, v163, v160, vcc
	v_cndmask_b32_e64 v160, v246, v248, s[98:99]
	v_cndmask_b32_e64 v161, v247, v249, s[98:99]
	v_cndmask_b32_e64 v162, v248, v246, s[98:99]
	v_cndmask_b32_e64 v163, v249, v247, s[98:99]
	v_cndmask_b32_e32 v246, v164, v165, vcc
	v_cndmask_b32_e32 v247, v165, v166, vcc
	v_cndmask_b32_e32 v248, v166, v167, vcc
	v_cndmask_b32_e32 v249, v167, v164, vcc
	v_cndmask_b32_e64 v164, v246, v248, s[98:99]
	v_cndmask_b32_e64 v165, v247, v249, s[98:99]
	v_cndmask_b32_e64 v166, v248, v246, s[98:99]
	v_cndmask_b32_e64 v167, v249, v247, s[98:99]
	v_cndmask_b32_e32 v246, v168, v169, vcc
	v_cndmask_b32_e32 v247, v169, v170, vcc
	v_cndmask_b32_e32 v248, v170, v171, vcc
	v_cndmask_b32_e32 v249, v171, v168, vcc
	v_cndmask_b32_e64 v168, v246, v248, s[98:99]
	v_cndmask_b32_e64 v169, v247, v249, s[98:99]
	v_cndmask_b32_e64 v170, v248, v246, s[98:99]
	v_cndmask_b32_e64 v171, v249, v247, s[98:99]
	s_waitcnt lgkmcnt(0)
	v_lshlrev_b32_e32 v88, 2, v172
	v_mul_u32_u24_e32 v172, 0x104, v173
	v_mad_i32_i24 v81, v93, s13, 0
	v_lshlrev_b32_e32 v172, 2, v172
	v_add3_u32 v173, v81, v88, v172
	v_and_b32_e32 v248, 3, v147
	v_add_u32_e32 v249, 0, v248
	v_and_b32_e32 v249, 3, v249
	v_mul_u32_u24_e32 v249, 0x820, v249
	v_add_u32_e32 v238, v173, v249
	v_add_u32_e32 v239, 0x410, v238
	v_add_u32_e32 v249, 1, v248
	v_and_b32_e32 v249, 3, v249
	v_mul_u32_u24_e32 v249, 0x820, v249
	v_add_u32_e32 v240, v173, v249
	v_add_u32_e32 v241, 0x410, v240
	v_add_u32_e32 v249, 2, v248
	v_and_b32_e32 v249, 3, v249
	v_mul_u32_u24_e32 v249, 0x820, v249
	v_add_u32_e32 v242, v173, v249
	v_add_u32_e32 v243, 0x410, v242
	v_add_u32_e32 v249, 3, v248
	v_and_b32_e32 v249, 3, v249
	v_mul_u32_u24_e32 v249, 0x820, v249
	v_add_u32_e32 v244, v173, v249
	v_add_u32_e32 v245, 0x410, v244
	s_mov_b32 s98, 0x5040100
	s_mov_b32 s99, 0x7060302
	v_perm_b32 v246, v98, v94, s98
	v_perm_b32 v247, v106, v102, s98
	ds_write2_b32 v238, v246, v247 offset1:32
	v_perm_b32 v94, v98, v94, s99
	v_perm_b32 v102, v106, v102, s99
	ds_write2_b32 v239, v94, v102 offset1:32
	v_perm_b32 v248, v99, v95, s98
	v_perm_b32 v249, v107, v103, s98
	ds_write2_b32 v240, v248, v249 offset1:32
	v_perm_b32 v95, v99, v95, s99
	v_perm_b32 v103, v107, v103, s99
	ds_write2_b32 v241, v95, v103 offset1:32
	v_perm_b32 v246, v100, v96, s98
	v_perm_b32 v247, v108, v104, s98
	ds_write2_b32 v242, v246, v247 offset1:32
	v_perm_b32 v96, v100, v96, s99
	v_perm_b32 v104, v108, v104, s99
	ds_write2_b32 v243, v96, v104 offset1:32
	v_perm_b32 v248, v101, v97, s98
	v_perm_b32 v249, v109, v105, s98
	ds_write2_b32 v244, v248, v249 offset1:32
	v_perm_b32 v97, v101, v97, s99
	v_perm_b32 v105, v109, v105, s99
	ds_write2_b32 v245, v97, v105 offset1:32
	v_perm_b32 v246, v114, v110, s98
	v_perm_b32 v247, v122, v118, s98
	ds_write2_b32 v238, v246, v247 offset0:64 offset1:96
	v_perm_b32 v110, v114, v110, s99
	v_perm_b32 v118, v122, v118, s99
	ds_write2_b32 v239, v110, v118 offset0:64 offset1:96
	v_perm_b32 v248, v115, v111, s98
	v_perm_b32 v249, v123, v119, s98
	ds_write2_b32 v240, v248, v249 offset0:64 offset1:96
	v_perm_b32 v111, v115, v111, s99
	v_perm_b32 v119, v123, v119, s99
	ds_write2_b32 v241, v111, v119 offset0:64 offset1:96
	v_perm_b32 v246, v116, v112, s98
	v_perm_b32 v247, v124, v120, s98
	ds_write2_b32 v242, v246, v247 offset0:64 offset1:96
	v_perm_b32 v112, v116, v112, s99
	v_perm_b32 v120, v124, v120, s99
	ds_write2_b32 v243, v112, v120 offset0:64 offset1:96
	v_perm_b32 v248, v117, v113, s98
	v_perm_b32 v249, v125, v121, s98
	ds_write2_b32 v244, v248, v249 offset0:64 offset1:96
	v_perm_b32 v113, v117, v113, s99
	v_perm_b32 v121, v125, v121, s99
	ds_write2_b32 v245, v113, v121 offset0:64 offset1:96
	v_perm_b32 v246, v130, v126, s98
	v_perm_b32 v247, v138, v134, s98
	ds_write2_b32 v238, v246, v247 offset0:128 offset1:160
	v_perm_b32 v126, v130, v126, s99
	v_perm_b32 v134, v138, v134, s99
	ds_write2_b32 v239, v126, v134 offset0:128 offset1:160
	v_perm_b32 v248, v131, v127, s98
	v_perm_b32 v249, v139, v135, s98
	ds_write2_b32 v240, v248, v249 offset0:128 offset1:160
	v_perm_b32 v127, v131, v127, s99
	v_perm_b32 v135, v139, v135, s99
	ds_write2_b32 v241, v127, v135 offset0:128 offset1:160
	v_perm_b32 v246, v132, v128, s98
	v_perm_b32 v247, v140, v136, s98
	ds_write2_b32 v242, v246, v247 offset0:128 offset1:160
	v_perm_b32 v128, v132, v128, s99
	v_perm_b32 v136, v140, v136, s99
	ds_write2_b32 v243, v128, v136 offset0:128 offset1:160
; #define MFMA16(a, b, c) __builtin_amdgcn_mfma_f32_16x16x32_bf16(a, b, c, 0, 0, 0)
; __device__ __forceinline__ void na2_task(const Params& p_, int l, int task, unsigned char* lds) {
;     ...
;     __syncthreads();
;     ...
; #pragma unroll
;         for (int i = 0; i < 8; ++i) { const int a = 4 * hf + i / 2, ci = i % 2, kt = a * 2 + ci;
;             f32x4 acc = {0.f, 0.f, 0.f, 0.f};
; #pragma unroll
;             for (int ks = 0; ks < 2; ++ks) acc = MFMA16(kfr[i][ks], qf[ks], acc);
;             const int dr = row_start + a - rq;
; #pragma unroll
;             for (int r = 0; r < 4; ++r) { const int kc = kst + 16 * ci + 4 * fq + r, rel = kc - col_start, dc = kc - c;
;                 float v = acc[r] * 0.125f + bi[(dr + 7) * 31 + min(max(dc + 15, 0), 30)];
	v_perm_b32 v248, v133, v129, s98
	v_perm_b32 v249, v141, v137, s98
	ds_write2_b32 v244, v248, v249 offset0:128 offset1:160
	v_perm_b32 v129, v133, v129, s99
	v_perm_b32 v137, v141, v137, s99
	ds_write2_b32 v245, v129, v137 offset0:128 offset1:160
	v_perm_b32 v246, v160, v142, s98
	v_perm_b32 v247, v168, v164, s98
	ds_write2_b32 v238, v246, v247 offset0:192 offset1:224
	v_perm_b32 v142, v160, v142, s99
	v_perm_b32 v164, v168, v164, s99
	ds_write2_b32 v239, v142, v164 offset0:192 offset1:224
	v_perm_b32 v248, v161, v143, s98
	v_perm_b32 v249, v169, v165, s98
	ds_write2_b32 v240, v248, v249 offset0:192 offset1:224
	v_perm_b32 v143, v161, v143, s99
	v_perm_b32 v165, v169, v165, s99
	ds_write2_b32 v241, v143, v165 offset0:192 offset1:224
	v_perm_b32 v246, v162, v144, s98
	v_perm_b32 v247, v170, v166, s98
	ds_write2_b32 v242, v246, v247 offset0:192 offset1:224
	v_perm_b32 v144, v162, v144, s99
	v_perm_b32 v166, v170, v166, s99
	ds_write2_b32 v243, v144, v166 offset0:192 offset1:224
	v_perm_b32 v248, v163, v145, s98
	v_perm_b32 v249, v171, v167, s98
	ds_write2_b32 v244, v248, v249 offset0:192 offset1:224
	v_perm_b32 v145, v163, v145, s99
	v_perm_b32 v167, v171, v167, s99
	ds_write2_b32 v245, v145, v167 offset0:192 offset1:224
	v_mfma_f32_16x16x32_bf16 v[62:65], v[62:65], v[6:9], 0
	s_sub_i32 s9, s12, s9
	v_mfma_f32_16x16x32_bf16 v[70:73], v[70:73], v[6:9], 0
	v_lshl_add_u32 v168, v92, 2, v80
	s_mulk_i32 s9, 0x7c
	v_add_u32_e32 v169, 16, v168
	s_add_i32 s9, s9, 0
	v_sub_u32_e32 v88, v169, v91
	s_add_i32 s9, s9, 0x20800
	v_mfma_f32_16x16x32_bf16 v[58:61], v[58:61], v[2:5], v[62:65]
	v_add_u32_e32 v173, 17, v168
	v_add_u32_e32 v174, 18, v168
	v_or_b32_e32 v170, 1, v168
	v_max_i32_e32 v62, -15, v88
	v_mfma_f32_16x16x32_bf16 v[94:97], v[66:69], v[2:5], v[70:73]
	v_mov_b32_e32 v66, s9
	s_movk_i32 s9, 0x744
	v_add_u32_e32 v62, 15, v62
	v_mad_i32_i24 v98, v93, s9, v66
	v_min_u32_e32 v62, 30, v62
	v_lshl_add_u32 v103, v62, 2, v98
	v_sub_u32_e32 v62, v173, v91
	v_mfma_f32_16x16x32_bf16 v[18:21], v[18:21], v[6:9], 0
	v_max_i32_e32 v62, -15, v62
	v_add_u32_e32 v62, 15, v62
	v_min_u32_e32 v62, 30, v62
	v_lshl_add_u32 v104, v62, 2, v98
	v_mfma_f32_16x16x32_bf16 v[62:65], v[10:13], v[2:5], v[18:21]
	v_sub_u32_e32 v10, v174, v91
	v_or_b32_e32 v171, 2, v168
	v_or_b32_e32 v172, 3, v168
	v_max_i32_e32 v18, -15, v10
	v_mfma_f32_16x16x32_bf16 v[10:13], v[38:41], v[6:9], 0
	v_add_u32_e32 v175, 19, v168
	v_sub_u32_e32 v66, v168, v91
	v_sub_u32_e32 v68, v170, v91
	v_mfma_f32_16x16x32_bf16 v[38:41], v[22:25], v[2:5], v[10:13]
	v_sub_u32_e32 v70, v171, v91
	v_sub_u32_e32 v72, v172, v91
	v_sub_u32_e32 v19, v175, v91
	v_mfma_f32_16x16x32_bf16 v[10:13], v[54:57], v[6:9], 0
	v_max_i32_e32 v66, -15, v66
	v_max_i32_e32 v68, -15, v68
	v_max_i32_e32 v70, -15, v70
	v_mfma_f32_16x16x32_bf16 v[42:45], v[42:45], v[2:5], v[10:13]
	v_max_i32_e32 v72, -15, v72
	v_max_i32_e32 v19, -15, v19
	v_add_u32_e32 v66, 15, v66
	v_mfma_f32_16x16x32_bf16 v[10:13], v[46:49], v[6:9], 0
	v_add_u32_e32 v68, 15, v68
	v_add_u32_e32 v70, 15, v70
	v_add_u32_e32 v72, 15, v72
	v_mfma_f32_16x16x32_bf16 v[46:49], v[30:33], v[2:5], v[10:13]
	v_add_u32_e32 v18, 15, v18
	v_add_u32_e32 v19, 15, v19
	v_lshlrev_b32_e32 v0, 3, v92
	v_mfma_f32_16x16x32_bf16 v[10:13], v[26:29], v[6:9], 0
	v_min_u32_e32 v66, 30, v66
	v_min_u32_e32 v68, 30, v68
	v_min_u32_e32 v70, 30, v70
	v_mfma_f32_16x16x32_bf16 v[54:57], v[14:17], v[2:5], v[10:13]
	v_min_u32_e32 v72, 30, v72
	v_min_u32_e32 v18, 30, v18
	v_min_u32_e32 v19, 30, v19
	v_mfma_f32_16x16x32_bf16 v[10:13], v[50:53], v[6:9], 0
	v_lshl_add_u32 v99, v66, 2, v98
	v_lshl_add_u32 v100, v68, 2, v98
	v_lshl_add_u32 v101, v70, 2, v98
	v_mfma_f32_16x16x32_bf16 v[50:53], v[34:37], v[2:5], v[10:13]
	v_lshl_add_u32 v102, v72, 2, v98
	v_lshl_add_u32 v18, v18, 2, v98
	v_lshl_add_u32 v19, v19, 2, v98
	s_nop 0
	v_lshl_add_u64 v[10:11], v[82:83], 0, s[44:45]
	v_mad_u64_u32 v[12:13], s[12:13], v10, s75, v[86:87]
	v_mov_b32_e32 v10, v13
	v_mad_u64_u32 v[10:11], s[12:13], v11, s75, v[10:11]
	v_mov_b32_e32 v13, v10
	v_lshl_add_u64 v[10:11], v[12:13], 0, v[76:77]
	v_mov_b32_e32 v12, v252
	v_mov_b32_e32 v13, v1
	v_add_u32_e32 v176, 0x400, v99
	v_add_u32_e32 v177, 0x400, v100
	v_add_u32_e32 v197, 0x400, v101
	v_add_u32_e32 v198, 0x400, v102
	v_add_u32_e32 v199, 0x400, v103
	v_add_u32_e32 v200, 0x400, v104
	v_add_u32_e32 v201, 0x400, v18
	v_add_u32_e32 v202, 0x400, v19
	v_lshl_add_u64 v[10:11], v[10:11], 0, v[12:13]
	ds_write_b32 v204, v203
	ds_write_b32 v205, v209
	s_waitcnt lgkmcnt(0)
	s_barrier
; #define MFMA16(a, b, c) __builtin_amdgcn_mfma_f32_16x16x32_bf16(a, b, c, 0, 0, 0)
; __device__ __forceinline__ void na2_task(const Params& p_, int l, int task, unsigned char* lds) {
;     ...
;             for (int i = 0; i < 8; ++i) { const int a = 4 + i / 2, ci = i % 2;
;                 const size_t ktok = (size_t)b * SEQ + (row_start + a) * 64 + kst + 16 * ci + fr;
; #pragma unroll
;                 for (int ks = 0; ks < 2; ++ks) kfr[i][ks] = *(const bf16x8v*)(Z + ktok * DIN + 3 * DG + h * 64 + 32 * ks + 8 * fq); }
;             asm volatile("" ::: "memory");
;         }
; #pragma unroll
;         for (int i = 0; i < 8; ++i) { const int a = 4 * hf + i / 2, ci = i % 2, kt = a * 2 + ci;
;             f32x4 acc = {0.f, 0.f, 0.f, 0.f};
; #pragma unroll
;             for (int ks = 0; ks < 2; ++ks) acc = MFMA16(kfr[i][ks], qf[ks], acc);
;             const int dr = row_start + a - rq;
; #pragma unroll
;             for (int r = 0; r < 4; ++r) { const int kc = kst + 16 * ci + 4 * fq + r, rel = kc - col_start, dc = kc - c;
;                 float v = acc[r] * 0.125f + bi[(dr + 7) * 31 + min(max(dc + 15, 0), 30)];
;                 v = (rel >= 0 && rel < 16) ? v : -1e30f; sc[kt][r] = v; mx = fmaxf(mx, v); } }
	ds_read2_b32 v[66:67], v99 offset0:217 offset1:248
	ds_read2_b32 v[68:69], v100 offset0:217 offset1:248
	ds_read2_b32 v[70:71], v101 offset0:217 offset1:248
	ds_read2_b32 v[72:73], v102 offset0:217 offset1:248
	ds_read2_b32 v[88:89], v103 offset0:217 offset1:248
	ds_read2_b32 v[92:93], v104 offset0:217 offset1:248
	ds_read2_b32 v[134:135], v18 offset0:217 offset1:248
	ds_read2_b32 v[136:137], v19 offset0:217 offset1:248
	ds_read2_b32 v[138:139], v176 offset0:23 offset1:54
	ds_read2_b32 v[140:141], v177 offset0:23 offset1:54
	ds_read2_b32 v[142:143], v197 offset0:23 offset1:54
	ds_read2_b32 v[144:145], v198 offset0:23 offset1:54
	ds_read2_b32 v[160:161], v199 offset0:23 offset1:54
	ds_read2_b32 v[162:163], v200 offset0:23 offset1:54
	ds_read2_b32 v[164:165], v201 offset0:23 offset1:54
	ds_read2_b32 v[166:167], v202 offset0:23 offset1:54
	s_nop 0
	s_nop 0
	v_lshl_add_u64 v[10:11], v[84:85], 0, s[44:45]
	v_mad_u64_u32 v[14:15], s[12:13], v10, s75, v[86:87]
	v_mov_b32_e32 v10, v15
	v_mad_u64_u32 v[10:11], s[12:13], v11, s75, v[10:11]
	v_mov_b32_e32 v15, v10
	v_lshl_add_u64 v[10:11], v[14:15], 0, v[76:77]
	v_lshl_add_u64 v[10:11], v[10:11], 0, v[12:13]
	s_nop 0
	s_nop 0
	v_lshl_add_u64 v[10:11], v[82:83], 0, s[42:43]
	v_mad_u64_u32 v[14:15], s[12:13], v10, s75, v[86:87]
	v_mov_b32_e32 v10, v15
	v_mad_u64_u32 v[10:11], s[12:13], v11, s75, v[10:11]
	v_mov_b32_e32 v15, v10
	v_lshl_add_u64 v[10:11], v[14:15], 0, v[76:77]
	v_lshl_add_u64 v[10:11], v[10:11], 0, v[12:13]
	s_nop 0
	s_nop 0
	v_lshl_add_u64 v[10:11], v[84:85], 0, s[42:43]
	v_mad_u64_u32 v[14:15], s[12:13], v10, s75, v[86:87]
	v_mov_b32_e32 v10, v15
	v_mad_u64_u32 v[10:11], s[12:13], v11, s75, v[10:11]
	v_mov_b32_e32 v15, v10
	v_lshl_add_u64 v[10:11], v[14:15], 0, v[76:77]
	v_lshl_add_u64 v[10:11], v[10:11], 0, v[12:13]
	s_nop 0
	global_load_dwordx4 v[126:129], v[10:11], off offset:3136
	v_lshl_add_u64 v[10:11], v[82:83], 0, s[40:41]
	v_mad_u64_u32 v[14:15], s[12:13], v10, s75, v[86:87]
	v_mov_b32_e32 v10, v15
	v_mad_u64_u32 v[10:11], s[12:13], v11, s75, v[10:11]
	v_mov_b32_e32 v15, v10
	v_lshl_add_u64 v[10:11], v[14:15], 0, v[76:77]
	v_lshl_add_u64 v[10:11], v[10:11], 0, v[12:13]
	global_load_dwordx4 v[130:133], v[10:11], off offset:3072
	global_load_dwordx4 v[34:37], v[10:11], off offset:3136
	v_lshl_add_u64 v[10:11], v[84:85], 0, s[40:41]
	v_mad_u64_u32 v[14:15], s[12:13], v10, s75, v[86:87]
	v_mov_b32_e32 v10, v15
	v_mad_u64_u32 v[10:11], s[12:13], v11, s75, v[10:11]
	v_mov_b32_e32 v15, v10
	v_lshl_add_u64 v[10:11], v[14:15], 0, v[76:77]
	v_lshl_add_u64 v[10:11], v[10:11], 0, v[12:13]
	global_load_dwordx4 v[30:33], v[10:11], off offset:3072
	global_load_dwordx4 v[26:29], v[10:11], off offset:3136
	v_lshl_add_u64 v[10:11], v[82:83], 0, s[24:25]
	v_mad_u64_u32 v[14:15], s[12:13], v10, s75, v[86:87]
	v_mov_b32_e32 v10, v15
	v_mad_u64_u32 v[10:11], s[12:13], v11, s75, v[10:11]
	v_mov_b32_e32 v15, v10
	v_lshl_add_u64 v[10:11], v[14:15], 0, v[76:77]
	v_lshl_add_u64 v[10:11], v[10:11], 0, v[12:13]
	global_load_dwordx4 v[22:25], v[10:11], off offset:3072
	global_load_dwordx4 v[18:21], v[10:11], off offset:3136
	v_lshl_add_u64 v[10:11], v[84:85], 0, s[24:25]
	v_mad_u64_u32 v[14:15], s[12:13], v10, s75, v[86:87]
	v_mov_b32_e32 v10, v15
	v_mad_u64_u32 v[10:11], s[12:13], v11, s75, v[10:11]
	v_mov_b32_e32 v15, v10
	v_sub_u32_e64 v82, v91, 8 clamp
	v_lshl_add_u64 v[10:11], v[14:15], 0, v[76:77]
	v_min_u32_e32 v82, 48, v82
	v_lshl_add_u64 v[10:11], v[10:11], 0, v[12:13]
	v_sub_u32_e32 v84, v171, v82
	global_load_dwordx4 v[14:17], v[10:11], off offset:3072
	s_nop 0
	global_load_dwordx4 v[10:13], v[10:11], off offset:3136
	v_cmp_gt_u32_e64 s[46:47], 16, v84
	v_sub_u32_e32 v84, v172, v82
	v_sub_u32_e32 v83, v168, v82
	v_cmp_gt_u32_e64 s[42:43], 16, v84
	v_sub_u32_e32 v84, v169, v82
	v_cmp_gt_u32_e32 vcc, 16, v83
	v_sub_u32_e32 v83, v170, v82
	s_waitcnt lgkmcnt(11)
	v_fmamk_f32 v58, v58, 0x3e000000, v88
	v_cmp_gt_u32_e64 s[44:45], 16, v84
	v_fmamk_f32 v66, v94, 0x3e000000, v66
	v_fmamk_f32 v68, v95, 0x3e000000, v68
	v_cmp_gt_u32_e64 s[40:41], 16, v83
	v_cndmask_b32_e64 v84, v194, v58, s[44:45]
	v_sub_u32_e32 v58, v173, v82
	v_cndmask_b32_e32 v66, v194, v66, vcc
	v_cndmask_b32_e64 v68, v194, v68, s[40:41]
	s_mov_b32 s9, 0xf149f2ca
	v_fmamk_f32 v70, v96, 0x3e000000, v70
	v_fmamk_f32 v72, v97, 0x3e000000, v72
	s_waitcnt lgkmcnt(10)
	v_fmamk_f32 v59, v59, 0x3e000000, v92
	v_cmp_gt_u32_e64 s[48:49], 16, v58
	v_max3_f32 v83, v66, s9, v68
	v_cndmask_b32_e64 v70, v194, v70, s[46:47]
	v_cndmask_b32_e64 v72, v194, v72, s[42:43]
	v_cndmask_b32_e64 v85, v194, v59, s[48:49]
	v_sub_u32_e32 v59, v174, v82
	v_max3_f32 v83, v83, v70, v72
	s_waitcnt lgkmcnt(9)
	v_fmamk_f32 v60, v60, 0x3e000000, v134
	v_cmp_gt_u32_e64 s[50:51], 16, v59
	v_sub_u32_e32 v59, v175, v82
	v_max3_f32 v58, v83, v84, v85
	v_cndmask_b32_e64 v83, v194, v60, s[50:51]
	s_waitcnt lgkmcnt(8)
	v_fmamk_f32 v60, v61, 0x3e000000, v136
	v_cmp_gt_u32_e64 s[52:53], 16, v59
	v_fmac_f32_e32 v67, 0x3e000000, v62
	v_fmac_f32_e32 v69, 0x3e000000, v63
	v_cndmask_b32_e64 v82, v194, v60, s[52:53]
	v_fmac_f32_e32 v93, 0x3e000000, v39
	s_waitcnt lgkmcnt(7)
	v_fmamk_f32 v39, v42, 0x3e000000, v138
	v_max3_f32 v58, v58, v83, v82
	v_cndmask_b32_e32 v62, v194, v67, vcc
	v_cndmask_b32_e64 v63, v194, v69, s[40:41]
	v_fmac_f32_e32 v71, 0x3e000000, v64
	v_fmac_f32_e32 v73, 0x3e000000, v65
	v_fmac_f32_e32 v89, 0x3e000000, v38
	v_cndmask_b32_e32 v88, v194, v39, vcc
	s_waitcnt lgkmcnt(6)
	v_fmamk_f32 v39, v43, 0x3e000000, v140
	v_max3_f32 v58, v58, v62, v63
	v_cndmask_b32_e64 v67, v194, v71, s[46:47]
	v_cndmask_b32_e64 v69, v194, v73, s[42:43]
	v_cndmask_b32_e64 v71, v194, v89, s[44:45]
	v_cndmask_b32_e64 v89, v194, v39, s[40:41]
	s_waitcnt lgkmcnt(5)
; #define MFMA16(a, b, c) __builtin_amdgcn_mfma_f32_16x16x32_bf16(a, b, c, 0, 0, 0)
; __device__ __forceinline__ void na2_task(const Params& p_, int l, int task, unsigned char* lds) {
;     ...
;             for (int i = 0; i < 8; ++i) { const int a = 4 + i / 2, ci = i % 2;
;                 const size_t ktok = (size_t)b * SEQ + (row_start + a) * 64 + kst + 16 * ci + fr;
; #pragma unroll
;                 for (int ks = 0; ks < 2; ++ks) kfr[i][ks] = *(const bf16x8v*)(Z + ktok * DIN + 3 * DG + h * 64 + 32 * ks + 8 * fq); }
;             asm volatile("" ::: "memory");
;         }
; #pragma unroll
;         for (int i = 0; i < 8; ++i) { const int a = 4 * hf + i / 2, ci = i % 2, kt = a * 2 + ci;
;             f32x4 acc = {0.f, 0.f, 0.f, 0.f};
; #pragma unroll
;             for (int ks = 0; ks < 2; ++ks) acc = MFMA16(kfr[i][ks], qf[ks], acc);
;             const int dr = row_start + a - rq;
; #pragma unroll
;             for (int r = 0; r < 4; ++r) { const int kc = kst + 16 * ci + 4 * fq + r, rel = kc - col_start, dc = kc - c;
;                 float v = acc[r] * 0.125f + bi[(dr + 7) * 31 + min(max(dc + 15, 0), 30)];
;                 v = (rel >= 0 && rel < 16) ? v : -1e30f; sc[kt][r] = v; mx = fmaxf(mx, v); } }
	v_fmamk_f32 v39, v44, 0x3e000000, v142
	v_max3_f32 v58, v58, v67, v69
	v_cndmask_b32_e64 v73, v194, v93, s[48:49]
	v_fmac_f32_e32 v135, 0x3e000000, v40
	v_fmac_f32_e32 v137, 0x3e000000, v41
	v_cndmask_b32_e64 v91, v194, v39, s[46:47]
	s_waitcnt lgkmcnt(4)
	v_fmamk_f32 v39, v45, 0x3e000000, v144
	v_max3_f32 v38, v58, v71, v73
	v_cndmask_b32_e64 v86, v194, v135, s[50:51]
	v_cndmask_b32_e64 v87, v194, v137, s[52:53]
	v_cndmask_b32_e64 v92, v194, v39, s[42:43]
	s_waitcnt lgkmcnt(3)
	v_fmamk_f32 v39, v46, 0x3e000000, v160
	v_max3_f32 v38, v38, v86, v87
	v_cndmask_b32_e64 v93, v194, v39, s[44:45]
	s_waitcnt lgkmcnt(2)
	v_fmamk_f32 v39, v47, 0x3e000000, v162
	v_max3_f32 v38, v38, v88, v89
	v_cndmask_b32_e64 v94, v194, v39, s[48:49]
	s_waitcnt lgkmcnt(1)
	v_fmamk_f32 v39, v48, 0x3e000000, v164
	v_max3_f32 v38, v38, v91, v92
	v_cndmask_b32_e64 v95, v194, v39, s[50:51]
	s_waitcnt lgkmcnt(0)
	v_fmamk_f32 v39, v49, 0x3e000000, v166
	v_max3_f32 v38, v38, v93, v94
	v_cndmask_b32_e64 v96, v194, v39, s[52:53]
	v_fmac_f32_e32 v139, 0x3e000000, v54
	v_fmac_f32_e32 v141, 0x3e000000, v55
	v_max3_f32 v38, v38, v95, v96
	v_cndmask_b32_e32 v97, v194, v139, vcc
	v_cndmask_b32_e64 v134, v194, v141, s[40:41]
	v_fmac_f32_e32 v143, 0x3e000000, v56
	v_fmac_f32_e32 v145, 0x3e000000, v57
	v_max3_f32 v38, v38, v97, v134
	v_cndmask_b32_e64 v135, v194, v143, s[46:47]
	v_cndmask_b32_e64 v136, v194, v145, s[42:43]
	v_fmac_f32_e32 v161, 0x3e000000, v50
	v_fmac_f32_e32 v163, 0x3e000000, v51
	v_max3_f32 v38, v38, v135, v136
	v_cndmask_b32_e64 v137, v194, v161, s[44:45]
	v_cndmask_b32_e64 v138, v194, v163, s[48:49]
	v_max3_f32 v42, v38, v137, v138
	s_waitcnt vmcnt(0)
	ds_bpermute_b32 v98, v251, v210
	ds_bpermute_b32 v99, v251, v211
	ds_bpermute_b32 v100, v251, v212
	ds_bpermute_b32 v101, v251, v213
	ds_bpermute_b32 v102, v251, v214
	ds_bpermute_b32 v103, v251, v215
	ds_bpermute_b32 v104, v251, v216
	ds_bpermute_b32 v105, v251, v217
	ds_bpermute_b32 v106, v251, v218
	ds_bpermute_b32 v107, v251, v219
	ds_bpermute_b32 v108, v251, v220
	ds_bpermute_b32 v109, v251, v221
	ds_bpermute_b32 v110, v251, v222
	ds_bpermute_b32 v111, v251, v223
	ds_bpermute_b32 v112, v251, v224
	ds_bpermute_b32 v113, v251, v225
	ds_bpermute_b32 v114, v251, v226
	ds_bpermute_b32 v115, v251, v227
	ds_bpermute_b32 v116, v251, v228
	ds_bpermute_b32 v117, v251, v229
	ds_bpermute_b32 v118, v251, v230
	ds_bpermute_b32 v119, v251, v231
	ds_bpermute_b32 v120, v251, v232
	ds_bpermute_b32 v121, v251, v233
	ds_bpermute_b32 v122, v251, v234
	ds_bpermute_b32 v123, v251, v235
	ds_bpermute_b32 v124, v251, v236
	ds_bpermute_b32 v125, v251, v237
	ds_bpermute_b32 v126, v251, v126
	ds_bpermute_b32 v127, v251, v127
	ds_bpermute_b32 v128, v251, v128
	ds_bpermute_b32 v129, v251, v129
	ds_bpermute_b32 v130, v251, v130
	ds_bpermute_b32 v131, v251, v131
	ds_bpermute_b32 v132, v251, v132
	ds_bpermute_b32 v133, v251, v133
	ds_bpermute_b32 v34, v251, v34
	ds_bpermute_b32 v35, v251, v35
	ds_bpermute_b32 v36, v251, v36
	ds_bpermute_b32 v37, v251, v37
	ds_bpermute_b32 v30, v251, v30
	ds_bpermute_b32 v31, v251, v31
	ds_bpermute_b32 v32, v251, v32
	ds_bpermute_b32 v33, v251, v33
	ds_bpermute_b32 v26, v251, v26
	ds_bpermute_b32 v27, v251, v27
	ds_bpermute_b32 v28, v251, v28
	ds_bpermute_b32 v29, v251, v29
	ds_bpermute_b32 v22, v251, v22
	ds_bpermute_b32 v23, v251, v23
	ds_bpermute_b32 v24, v251, v24
	ds_bpermute_b32 v25, v251, v25
	ds_bpermute_b32 v18, v251, v18
	ds_bpermute_b32 v19, v251, v19
	ds_bpermute_b32 v20, v251, v20
	ds_bpermute_b32 v21, v251, v21
	ds_bpermute_b32 v14, v251, v14
	ds_bpermute_b32 v15, v251, v15
	ds_bpermute_b32 v16, v251, v16
	ds_bpermute_b32 v17, v251, v17
	ds_bpermute_b32 v10, v251, v10
	ds_bpermute_b32 v11, v251, v11
	ds_bpermute_b32 v12, v251, v12
	ds_bpermute_b32 v13, v251, v13
	s_waitcnt lgkmcnt(0)
	v_mfma_f32_16x16x32_bf16 v[38:41], v[98:101], v[6:9], 0
	ds_read2_b32 v[46:47], v176 offset0:85 offset1:116
	ds_read2_b32 v[48:49], v177 offset0:85 offset1:116
	ds_read2_b32 v[50:51], v197 offset0:85 offset1:116
	s_waitcnt vmcnt(14)
	v_mfma_f32_16x16x32_bf16 v[38:41], v[102:105], v[2:5], v[38:41]
	v_fmac_f32_e32 v165, 0x3e000000, v52
	v_fmac_f32_e32 v167, 0x3e000000, v53
	ds_read2_b32 v[52:53], v198 offset0:85 offset1:116
	ds_read2_b32 v[54:55], v199 offset0:85 offset1:116
	ds_read2_b32 v[56:57], v200 offset0:85 offset1:116
	s_waitcnt lgkmcnt(5)
	s_nop 1
	v_fmamk_f32 v38, v38, 0x3e000000, v46
	v_cndmask_b32_e32 v98, v194, v38, vcc
	s_waitcnt lgkmcnt(4)
	v_fmamk_f32 v38, v39, 0x3e000000, v48
	v_cndmask_b32_e64 v48, v194, v38, s[40:41]
	s_waitcnt lgkmcnt(3)
	v_fmamk_f32 v38, v40, 0x3e000000, v50
	v_cndmask_b32_e64 v50, v194, v38, s[46:47]
	s_waitcnt lgkmcnt(2)
	v_fmamk_f32 v38, v41, 0x3e000000, v52
	v_cndmask_b32_e64 v52, v194, v38, s[42:43]
	s_waitcnt vmcnt(13)
	v_mfma_f32_16x16x32_bf16 v[38:41], v[106:109], v[6:9], 0
	v_cndmask_b32_e64 v139, v194, v165, s[50:51]
	v_cndmask_b32_e64 v140, v194, v167, s[52:53]
	ds_read2_b32 v[58:59], v201 offset0:85 offset1:116
	s_waitcnt vmcnt(12)
	v_mfma_f32_16x16x32_bf16 v[38:41], v[110:113], v[2:5], v[38:41]
	v_max3_f32 v42, v42, v139, v140
	ds_read2_b32 v[60:61], v202 offset0:85 offset1:116
	v_max3_f32 v42, v42, v98, v48
	v_max3_f32 v42, v42, v50, v52
	s_waitcnt vmcnt(5)
	v_mfma_f32_16x16x32_bf16 v[30:33], v[30:33], v[6:9], 0
	s_waitcnt lgkmcnt(3)
	s_nop 0
	v_fmamk_f32 v38, v38, 0x3e000000, v54
	v_cndmask_b32_e64 v54, v194, v38, s[44:45]
	s_waitcnt lgkmcnt(2)
	v_fmamk_f32 v38, v39, 0x3e000000, v56
	v_cndmask_b32_e64 v99, v194, v38, s[48:49]
	v_max3_f32 v38, v42, v54, v99
	v_mfma_f32_16x16x32_bf16 v[42:45], v[114:117], v[6:9], 0
	s_waitcnt lgkmcnt(1)
; #define MFMA16(a, b, c) __builtin_amdgcn_mfma_f32_16x16x32_bf16(a, b, c, 0, 0, 0)
; __device__ __forceinline__ void na2_task(const Params& p_, int l, int task, unsigned char* lds) {
;     ...
; #pragma unroll
;         for (int i = 0; i < 8; ++i) { const int a = 4 * hf + i / 2, ci = i % 2, kt = a * 2 + ci;
;             f32x4 acc = {0.f, 0.f, 0.f, 0.f};
; #pragma unroll
;             for (int ks = 0; ks < 2; ++ks) acc = MFMA16(kfr[i][ks], qf[ks], acc);
;             const int dr = row_start + a - rq;
; #pragma unroll
;             for (int r = 0; r < 4; ++r) { const int kc = kst + 16 * ci + 4 * fq + r, rel = kc - col_start, dc = kc - c;
;                 float v = acc[r] * 0.125f + bi[(dr + 7) * 31 + min(max(dc + 15, 0), 30)];
;                 v = (rel >= 0 && rel < 16) ? v : -1e30f; sc[kt][r] = v; mx = fmaxf(mx, v); } }
;     }
;     mx = fmaxf(mx, __shfl_xor(mx, 16)); mx = fmaxf(mx, __shfl_xor(mx, 32));
	v_fmamk_f32 v39, v40, 0x3e000000, v58
	v_cndmask_b32_e64 v100, v194, v39, s[50:51]
	s_waitcnt lgkmcnt(0)
	v_fmamk_f32 v39, v41, 0x3e000000, v60
	v_cndmask_b32_e64 v101, v194, v39, s[52:53]
	v_max3_f32 v46, v38, v100, v101
	v_mfma_f32_16x16x32_bf16 v[38:41], v[118:121], v[2:5], v[42:45]
	v_lshl_add_u64 v[78:79], v[78:79], 0, v[0:1]
	s_mov_b32 s9, 0x12d20000
	v_mfma_f32_16x16x32_bf16 v[42:45], v[122:125], v[6:9], 0
	s_waitcnt vmcnt(4)
	v_mfma_f32_16x16x32_bf16 v[26:29], v[26:29], v[2:5], v[30:33]
	s_nop 2
	v_fmac_f32_e32 v47, 0x3e000000, v38
	v_fmac_f32_e32 v49, 0x3e000000, v39
	v_cndmask_b32_e32 v102, v194, v47, vcc
	v_cndmask_b32_e64 v49, v194, v49, s[40:41]
	v_fmac_f32_e32 v51, 0x3e000000, v40
	v_fmac_f32_e32 v53, 0x3e000000, v41
	v_max3_f32 v38, v46, v102, v49
	v_cndmask_b32_e64 v51, v194, v51, s[46:47]
	v_cndmask_b32_e64 v53, v194, v53, s[42:43]
	v_max3_f32 v46, v38, v51, v53
	v_mfma_f32_16x16x32_bf16 v[38:41], v[126:129], v[2:5], v[42:45]
	s_waitcnt vmcnt(3)
	v_mfma_f32_16x16x32_bf16 v[22:25], v[22:25], v[6:9], 0
	s_waitcnt vmcnt(2)
	v_mfma_f32_16x16x32_bf16 v[18:21], v[18:21], v[2:5], v[22:25]
	s_nop 3
	v_fmac_f32_e32 v55, 0x3e000000, v38
	v_fmac_f32_e32 v57, 0x3e000000, v39
	v_fmac_f32_e32 v59, 0x3e000000, v40
	v_fmac_f32_e32 v61, 0x3e000000, v41
	v_mfma_f32_16x16x32_bf16 v[38:41], v[130:133], v[6:9], 0
	v_cndmask_b32_e64 v55, v194, v55, s[44:45]
	v_cndmask_b32_e64 v103, v194, v57, s[48:49]
	v_max3_f32 v42, v46, v55, v103
	v_cndmask_b32_e64 v104, v194, v59, s[50:51]
	v_cndmask_b32_e64 v105, v194, v61, s[52:53]
	v_max3_f32 v46, v42, v104, v105
	ds_read2_b32 v[42:43], v176 offset0:147 offset1:178
	ds_read2_b32 v[44:45], v177 offset0:147 offset1:178
	v_mfma_f32_16x16x32_bf16 v[34:37], v[34:37], v[2:5], v[38:41]
	s_waitcnt lgkmcnt(1)
	v_fmac_f32_e32 v43, 0x3e000000, v18
	s_nop 0
	ds_read2_b32 v[38:39], v197 offset0:147 offset1:178
	s_waitcnt vmcnt(1)
	v_mfma_f32_16x16x32_bf16 v[6:9], v[14:17], v[6:9], 0
	s_nop 1
	v_fmamk_f32 v34, v34, 0x3e000000, v42
	v_cndmask_b32_e32 v42, v194, v34, vcc
	s_waitcnt lgkmcnt(1)
	v_fmamk_f32 v40, v35, 0x3e000000, v44
	ds_read2_b32 v[34:35], v198 offset0:147 offset1:178
	v_cndmask_b32_e64 v44, v194, v40, s[40:41]
	s_waitcnt lgkmcnt(1)
	v_fmamk_f32 v36, v36, 0x3e000000, v38
	v_max3_f32 v40, v46, v42, v44
	v_cndmask_b32_e64 v38, v194, v36, s[46:47]
	s_waitcnt lgkmcnt(0)
	v_fmamk_f32 v34, v37, 0x3e000000, v34
	v_cndmask_b32_e64 v34, v194, v34, s[42:43]
	v_max3_f32 v46, v40, v38, v34
	ds_read2_b32 v[36:37], v199 offset0:147 offset1:178
	ds_read2_b32 v[40:41], v200 offset0:147 offset1:178
	ds_read2_b32 v[30:31], v201 offset0:147 offset1:178
	s_waitcnt vmcnt(0)
	v_mfma_f32_16x16x32_bf16 v[2:5], v[10:13], v[2:5], v[6:9]
	v_fmac_f32_e32 v45, 0x3e000000, v19
	s_waitcnt lgkmcnt(2)
	v_fmamk_f32 v26, v26, 0x3e000000, v36
	v_cndmask_b32_e64 v36, v194, v26, s[44:45]
	s_waitcnt lgkmcnt(1)
	v_fmamk_f32 v26, v27, 0x3e000000, v40
	v_cndmask_b32_e64 v40, v194, v26, s[48:49]
	ds_read2_b32 v[26:27], v202 offset0:147 offset1:178
	s_waitcnt lgkmcnt(1)
	v_fmamk_f32 v28, v28, 0x3e000000, v30
	v_max3_f32 v32, v46, v36, v40
	v_cndmask_b32_e64 v106, v194, v28, s[50:51]
	v_cndmask_b32_e32 v43, v194, v43, vcc
	s_waitcnt lgkmcnt(0)
	v_fmamk_f32 v26, v29, 0x3e000000, v26
	v_cndmask_b32_e64 v107, v194, v26, s[52:53]
	v_max3_f32 v26, v32, v106, v107
	v_cndmask_b32_e64 v45, v194, v45, s[40:41]
	v_fmac_f32_e32 v39, 0x3e000000, v20
	v_fmac_f32_e32 v35, 0x3e000000, v21
	v_fmac_f32_e32 v31, 0x3e000000, v4
	v_and_b32_e32 v4, 64, v178
	v_max3_f32 v18, v26, v43, v45
	v_cndmask_b32_e64 v39, v194, v39, s[46:47]
	v_cndmask_b32_e64 v108, v194, v35, s[42:43]
	v_fmac_f32_e32 v37, 0x3e000000, v2
	v_fmac_f32_e32 v41, 0x3e000000, v3
	v_xor_b32_e32 v3, 16, v178
	v_add_u32_e32 v4, 64, v4
	v_max3_f32 v14, v18, v39, v108
	v_cndmask_b32_e64 v109, v194, v37, s[44:45]
	v_cndmask_b32_e64 v41, v194, v41, s[48:49]
	v_fmac_f32_e32 v27, 0x3e000000, v5
	v_cmp_lt_i32_e32 vcc, v3, v4
	v_max3_f32 v2, v14, v109, v41
	v_cndmask_b32_e64 v110, v194, v31, s[50:51]
	v_cndmask_b32_e64 v111, v194, v27, s[52:53]
	v_cndmask_b32_e32 v3, v178, v3, vcc
	v_max3_f32 v2, v2, v110, v111
	v_lshlrev_b32_e32 v112, 2, v3
	ds_bpermute_b32 v3, v112, v2
	s_waitcnt lgkmcnt(0)
	v_max_f32_e32 v3, v3, v3
	v_max_f32_e32 v2, v2, v3
	v_xor_b32_e32 v3, 32, v178
	v_cmp_lt_i32_e32 vcc, v3, v4
	s_nop 1
	v_cndmask_b32_e32 v3, v178, v3, vcc
	v_lshlrev_b32_e32 v113, 2, v3
	ds_bpermute_b32 v3, v113, v2
	s_waitcnt lgkmcnt(0)
; __device__ __forceinline__ unsigned pk2(float lo, float hi) { return f2bf(lo) | (f2bf(hi) << 16); }
; __device__ __forceinline__ void na2_task(const Params& p_, int l, int task, unsigned char* lds) {
;     ...
;     float sum = 0.f; unsigned pp[16][2];
; #pragma unroll
;     for (int kt = 0; kt < 16; ++kt) { const float e0 = __expf(sc[kt][0] - mx), e1 = __expf(sc[kt][1] - mx), e2 = __expf(sc[kt][2] - mx), e3 = __expf(sc[kt][3] - mx);
;         sum += (e0 + e1) + (e2 + e3); pp[kt][0] = pk2(e0, e1); pp[kt][1] = pk2(e2, e3); }
	v_max_f32_e32 v3, v3, v3
	v_max_f32_e32 v114, v2, v3
	v_sub_f32_e32 v6, v84, v114
	v_mul_f32_e32 v6, 0x3fb8aa3b, v6
	v_sub_f32_e32 v3, v68, v114
	v_exp_f32_e32 v60, v6
	v_sub_f32_e32 v6, v85, v114
	v_mul_f32_e32 v3, 0x3fb8aa3b, v3
	v_mul_f32_e32 v6, 0x3fb8aa3b, v6
	v_sub_f32_e32 v2, v66, v114
	v_exp_f32_e32 v4, v3
	v_sub_f32_e32 v3, v70, v114
	v_sub_f32_e32 v5, v72, v114
	v_exp_f32_e32 v64, v6
	v_sub_f32_e32 v6, v83, v114
	v_mul_f32_e32 v2, 0x3fb8aa3b, v2
	v_mul_f32_e32 v3, 0x3fb8aa3b, v3
	v_mul_f32_e32 v5, 0x3fb8aa3b, v5
	v_mul_f32_e32 v6, 0x3fb8aa3b, v6
	v_exp_f32_e32 v2, v2
	v_exp_f32_e32 v3, v3
	v_exp_f32_e32 v5, v5
	v_exp_f32_e32 v61, v6
	v_sub_f32_e32 v6, v82, v114
	v_mul_f32_e32 v6, 0x3fb8aa3b, v6
	v_exp_f32_e32 v65, v6
	v_pk_add_f32 v[6:7], v[2:3], v[4:5]
	v_sub_f32_e32 v8, v87, v114
	v_add_f32_e32 v6, v6, v7
	v_add_f32_e32 v9, 0, v6
	v_pk_add_f32 v[6:7], v[60:61], v[64:65]
	v_mul_f32_e32 v8, 0x3fb8aa3b, v8
	v_pk_add_f32 v[6:7], v[6:7], v[6:7] op_sel_hi:[0,1]
	v_sub_f32_e32 v6, v62, v114
	v_mul_f32_e32 v6, 0x3fb8aa3b, v6
	v_exp_f32_e32 v84, v6
	v_sub_f32_e32 v6, v63, v114
	v_mul_f32_e32 v6, 0x3fb8aa3b, v6
	v_exp_f32_e32 v85, v6
	v_sub_f32_e32 v6, v67, v114
	v_mul_f32_e32 v6, 0x3fb8aa3b, v6
	v_exp_f32_e32 v115, v6
	v_sub_f32_e32 v6, v69, v114
	v_mul_f32_e32 v6, 0x3fb8aa3b, v6
	v_exp_f32_e32 v116, v6
	v_sub_f32_e32 v6, v71, v114
	v_mul_f32_e32 v6, 0x3fb8aa3b, v6
	v_exp_f32_e32 v12, v6
	v_sub_f32_e32 v6, v73, v114
	v_mul_f32_e32 v6, 0x3fb8aa3b, v6
	v_exp_f32_e32 v62, v6
	v_sub_f32_e32 v6, v86, v114
	v_mul_f32_e32 v6, 0x3fb8aa3b, v6
	v_exp_f32_e32 v6, v6
	v_exp_f32_e32 v8, v8
	v_add_f32_e32 v13, v84, v85
	v_add_f32_e32 v63, v115, v116
	v_pk_add_f32 v[10:11], v[12:13], v[62:63]
	v_pk_add_f32 v[14:15], v[6:7], v[8:9]
	v_sub_f32_e32 v7, v88, v114
	v_pk_add_f32 v[10:11], v[10:11], v[14:15]
	v_mul_f32_e32 v7, 0x3fb8aa3b, v7
	v_pk_add_f32 v[14:15], v[10:11], v[10:11] op_sel_hi:[0,1]
	v_exp_f32_e32 v10, v7
	v_sub_f32_e32 v7, v89, v114
	v_mul_f32_e32 v7, 0x3fb8aa3b, v7
	v_exp_f32_e32 v58, v7
	v_sub_f32_e32 v7, v91, v114
	v_mul_f32_e32 v7, 0x3fb8aa3b, v7
	v_exp_f32_e32 v11, v7
	v_sub_f32_e32 v7, v92, v114
	v_mul_f32_e32 v7, 0x3fb8aa3b, v7
	v_exp_f32_e32 v59, v7
	v_sub_f32_e32 v7, v93, v114
	v_mul_f32_e32 v7, 0x3fb8aa3b, v7
	v_exp_f32_e32 v13, v7
	v_sub_f32_e32 v7, v94, v114
	v_mul_f32_e32 v7, 0x3fb8aa3b, v7
	v_exp_f32_e32 v86, v7
	v_sub_f32_e32 v7, v95, v114
	v_mul_f32_e32 v7, 0x3fb8aa3b, v7
	v_exp_f32_e32 v87, v7
	v_sub_f32_e32 v7, v96, v114
	v_mul_f32_e32 v7, 0x3fb8aa3b, v7
	v_exp_f32_e32 v88, v7
	v_sub_f32_e32 v7, v97, v114
	v_pk_add_f32 v[16:17], v[10:11], v[58:59]
	v_mul_f32_e32 v7, 0x3fb8aa3b, v7
	v_pk_add_f32 v[18:19], v[16:17], v[16:17] op_sel_hi:[0,1]
	v_exp_f32_e32 v16, v7
	v_sub_f32_e32 v7, v134, v114
	v_mul_f32_e32 v7, 0x3fb8aa3b, v7
	v_exp_f32_e32 v20, v7
	v_sub_f32_e32 v7, v135, v114
	v_mul_f32_e32 v7, 0x3fb8aa3b, v7
	v_exp_f32_e32 v18, v7
	v_sub_f32_e32 v7, v136, v114
	v_mul_f32_e32 v7, 0x3fb8aa3b, v7
	v_exp_f32_e32 v14, v7
	v_sub_f32_e32 v7, v137, v114
	v_mul_f32_e32 v7, 0x3fb8aa3b, v7
	v_exp_f32_e32 v68, v7
	v_sub_f32_e32 v7, v138, v114
	v_mul_f32_e32 v7, 0x3fb8aa3b, v7
	v_exp_f32_e32 v72, v7
	v_sub_f32_e32 v7, v139, v114
	v_mul_f32_e32 v7, 0x3fb8aa3b, v7
	v_exp_f32_e32 v69, v7
	v_sub_f32_e32 v7, v140, v114
	v_mul_f32_e32 v7, 0x3fb8aa3b, v7
	v_exp_f32_e32 v73, v7
	v_sub_f32_e32 v7, v98, v114
	v_mul_f32_e32 v7, 0x3fb8aa3b, v7
	v_pk_add_f32 v[24:25], v[18:19], v[14:15]
	v_exp_f32_e32 v19, v7
	v_sub_f32_e32 v7, v48, v114
	v_add_f32_e32 v17, v13, v86
	v_add_f32_e32 v21, v87, v88
	v_mul_f32_e32 v7, 0x3fb8aa3b, v7
	v_pk_add_f32 v[22:23], v[16:17], v[20:21]
	v_exp_f32_e32 v21, v7
	v_sub_f32_e32 v7, v50, v114
	v_mul_f32_e32 v7, 0x3fb8aa3b, v7
	v_exp_f32_e32 v89, v7
	v_sub_f32_e32 v7, v52, v114
	v_mul_f32_e32 v7, 0x3fb8aa3b, v7
	v_exp_f32_e32 v91, v7
	v_sub_f32_e32 v7, v54, v114
	v_mul_f32_e32 v7, 0x3fb8aa3b, v7
	v_exp_f32_e32 v66, v7
	v_sub_f32_e32 v7, v99, v114
	v_pk_add_f32 v[22:23], v[22:23], v[24:25]
	v_mul_f32_e32 v7, 0x3fb8aa3b, v7
	v_pk_add_f32 v[56:57], v[22:23], v[22:23] op_sel_hi:[0,1]
	v_pk_add_f32 v[22:23], v[68:69], v[72:73]
	v_exp_f32_e32 v70, v7
	v_sub_f32_e32 v7, v100, v114
	v_pk_add_f32 v[46:47], v[22:23], v[22:23] op_sel_hi:[0,1]
	v_mul_f32_e32 v7, 0x3fb8aa3b, v7
	v_exp_f32_e32 v46, v7
	v_sub_f32_e32 v7, v101, v114
	v_mul_f32_e32 v7, 0x3fb8aa3b, v7
	v_exp_f32_e32 v56, v7
	v_add_f32_e32 v67, v19, v21
	v_add_f32_e32 v71, v89, v91
	v_pk_add_f32 v[22:23], v[66:67], v[70:71]
	v_pk_add_f32 v[24:25], v[46:47], v[56:57]
	v_sub_f32_e32 v7, v102, v114
	v_pk_add_f32 v[22:23], v[22:23], v[24:25]
	v_mul_f32_e32 v7, 0x3fb8aa3b, v7
	v_pk_add_f32 v[26:27], v[22:23], v[22:23] op_sel_hi:[0,1]
	v_exp_f32_e32 v22, v7
	v_sub_f32_e32 v7, v49, v114
	v_mul_f32_e32 v7, 0x3fb8aa3b, v7
	v_exp_f32_e32 v24, v7
	v_sub_f32_e32 v7, v51, v114
	v_mul_f32_e32 v7, 0x3fb8aa3b, v7
	v_exp_f32_e32 v23, v7
	v_sub_f32_e32 v7, v53, v114
	v_mul_f32_e32 v7, 0x3fb8aa3b, v7
	v_exp_f32_e32 v25, v7
	v_sub_f32_e32 v7, v55, v114
	v_mul_f32_e32 v7, 0x3fb8aa3b, v7
	v_exp_f32_e32 v67, v7
	v_sub_f32_e32 v7, v103, v114
	v_mul_f32_e32 v7, 0x3fb8aa3b, v7
	v_exp_f32_e32 v71, v7
	v_sub_f32_e32 v7, v104, v114
	v_mul_f32_e32 v7, 0x3fb8aa3b, v7
	v_exp_f32_e32 v92, v7
	v_sub_f32_e32 v7, v105, v114
	v_mul_f32_e32 v7, 0x3fb8aa3b, v7
	v_exp_f32_e32 v93, v7
	v_sub_f32_e32 v7, v42, v114
	v_pk_add_f32 v[28:29], v[22:23], v[24:25]
	v_mul_f32_e32 v7, 0x3fb8aa3b, v7
	v_pk_add_f32 v[30:31], v[28:29], v[28:29] op_sel_hi:[0,1]
	v_exp_f32_e32 v28, v7
	v_sub_f32_e32 v7, v44, v114
	v_mul_f32_e32 v7, 0x3fb8aa3b, v7
	v_exp_f32_e32 v32, v7
	v_sub_f32_e32 v7, v38, v114
	v_mul_f32_e32 v7, 0x3fb8aa3b, v7
; __device__ __forceinline__ unsigned pk2(float lo, float hi) { return f2bf(lo) | (f2bf(hi) << 16); }
; #define MFMA16(a, b, c) __builtin_amdgcn_mfma_f32_16x16x32_bf16(a, b, c, 0, 0, 0)
; __device__ __forceinline__ void na2_task(const Params& p_, int l, int task, unsigned char* lds) {
;     ...
;     float sum = 0.f; unsigned pp[16][2];
; #pragma unroll
;     for (int kt = 0; kt < 16; ++kt) { const float e0 = __expf(sc[kt][0] - mx), e1 = __expf(sc[kt][1] - mx), e2 = __expf(sc[kt][2] - mx), e3 = __expf(sc[kt][3] - mx);
;         sum += (e0 + e1) + (e2 + e3); pp[kt][0] = pk2(e0, e1); pp[kt][1] = pk2(e2, e3); }
;     sum += __shfl_xor(sum, 16); sum += __shfl_xor(sum, 32);
;     const float inv = 1.f / sum;
;     const bf16* VTh = VT + (size_t)hh * 64 * 520;
; #pragma unroll
;     for (int dt = 0; dt < 4; ++dt) { f32x4 o = {0.f, 0.f, 0.f, 0.f};
; #pragma unroll
;         for (int t = 0; t < 8; ++t) { const int k0 = 2 * t, k1 = 2 * t + 1, a0 = k0 / 2, c0 = k0 % 2, a1 = k1 / 2, c1 = k1 % 2;
;             const u32x2 vlo = *(const u32x2*)(VTh + (16 * dt + fr) * 520 + a0 * 64 + kst + 16 * c0 + 4 * fq), vhi = *(const u32x2*)(VTh + (16 * dt + fr) * 520 + a1 * 64 + kst + 16 * c1 + 4 * fq);
;             o = MFMA16(mk8(vlo.x, vlo.y, vhi.x, vhi.y), mk8(pp[k0][0], pp[k0][1], pp[k1][0], pp[k1][1]), o); }
	v_exp_f32_e32 v30, v7
	v_sub_f32_e32 v7, v34, v114
	v_mul_f32_e32 v7, 0x3fb8aa3b, v7
	v_exp_f32_e32 v26, v7
	v_sub_f32_e32 v7, v36, v114
	v_mul_f32_e32 v7, 0x3fb8aa3b, v7
	v_exp_f32_e32 v48, v7
	v_sub_f32_e32 v7, v40, v114
	v_mul_f32_e32 v7, 0x3fb8aa3b, v7
	v_exp_f32_e32 v52, v7
	v_sub_f32_e32 v7, v106, v114
	v_mul_f32_e32 v7, 0x3fb8aa3b, v7
	v_exp_f32_e32 v49, v7
	v_sub_f32_e32 v7, v107, v114
	v_mul_f32_e32 v7, 0x3fb8aa3b, v7
	v_exp_f32_e32 v53, v7
	v_sub_f32_e32 v7, v43, v114
	v_mul_f32_e32 v7, 0x3fb8aa3b, v7
	v_pk_add_f32 v[36:37], v[30:31], v[26:27]
	v_exp_f32_e32 v31, v7
	v_sub_f32_e32 v7, v45, v114
	v_add_f32_e32 v29, v67, v71
	v_add_f32_e32 v33, v92, v93
	v_mul_f32_e32 v7, 0x3fb8aa3b, v7
	v_pk_add_f32 v[34:35], v[28:29], v[32:33]
	v_exp_f32_e32 v33, v7
	v_sub_f32_e32 v7, v39, v114
	v_mul_f32_e32 v7, 0x3fb8aa3b, v7
	v_exp_f32_e32 v94, v7
	v_sub_f32_e32 v7, v108, v114
	v_mul_f32_e32 v7, 0x3fb8aa3b, v7
	v_exp_f32_e32 v95, v7
	v_sub_f32_e32 v7, v109, v114
	v_mul_f32_e32 v7, 0x3fb8aa3b, v7
	v_exp_f32_e32 v50, v7
	v_sub_f32_e32 v7, v41, v114
	v_pk_add_f32 v[34:35], v[34:35], v[36:37]
	v_mul_f32_e32 v7, 0x3fb8aa3b, v7
	v_pk_add_f32 v[36:37], v[34:35], v[34:35] op_sel_hi:[0,1]
	v_pk_add_f32 v[34:35], v[48:49], v[52:53]
	v_exp_f32_e32 v54, v7
	v_sub_f32_e32 v7, v110, v114
	v_pk_add_f32 v[34:35], v[34:35], v[34:35] op_sel_hi:[0,1]
	v_mul_f32_e32 v7, 0x3fb8aa3b, v7
	v_exp_f32_e32 v34, v7
	v_sub_f32_e32 v7, v111, v114
	v_mul_f32_e32 v7, 0x3fb8aa3b, v7
	v_exp_f32_e32 v36, v7
	v_add_f32_e32 v51, v31, v33
	v_add_f32_e32 v55, v94, v95
	v_pk_add_f32 v[38:39], v[50:51], v[54:55]
	v_pk_add_f32 v[40:41], v[34:35], v[36:37]
	s_nop 0
	v_pk_add_f32 v[38:39], v[38:39], v[40:41]
	s_nop 0
	v_add_f32_e32 v7, v38, v39
	ds_bpermute_b32 v9, v112, v7
	v_lshlrev_b64 v[38:39], 12, v[74:75]
	v_lshl_add_u64 v[38:39], s[62:63], 0, v[38:39]
	v_lshl_add_u64 v[38:39], v[38:39], 0, v[76:77]
	v_lshl_add_u64 v[42:43], v[38:39], 0, v[0:1]
	s_waitcnt lgkmcnt(0)
	v_add_f32_e32 v7, v7, v9
	ds_bpermute_b32 v9, v113, v7
	s_nop 0
	s_nop 0
	s_nop 0
	s_nop 0
	s_waitcnt lgkmcnt(0)
	v_add_f32_e32 v7, v7, v9
	v_div_scale_f32 v9, s[12:13], v7, v7, 1.0
	v_rcp_f32_e32 v15, v9
	s_nop 0
	s_nop 0
	s_mov_b64 s[12:13], 0x1400
	v_fma_f32 v17, -v9, v15, 1.0
	v_fmac_f32_e32 v15, v17, v15
	v_div_scale_f32 v17, vcc, 1.0, v7, 1.0
	v_mul_f32_e32 v27, v17, v15
	v_fma_f32 v29, -v9, v27, v17
	v_fmac_f32_e32 v27, v29, v15
	v_fma_f32 v9, -v9, v27, v17
	v_div_fmas_f32 v9, v9, v15, v27
	v_div_fixup_f32 v40, v9, v7, 1.0
	v_lshl_add_u32 v7, v80, 1, v81
	v_mul_u32_u24_e32 v9, 0x410, v90
	v_add3_u32 v0, v7, v9, v0
	s_nop 0
	s_nop 0
	v_bfe_u32 v15, v5, 16, 1
	v_bfe_u32 v17, v4, 16, 1
	v_cvt_pk_bf16_f32 v207, v60, v64
	v_cvt_pk_bf16_f32 v206, v61, v65
	v_add3_u32 v17, v4, v17, s14
	v_add3_u32 v15, v5, v15, s14
	s_nop 0
	s_nop 0
	v_bfe_u32 v7, v2, 16, 1
	v_bfe_u32 v9, v3, 16, 1
	s_nop 0
	s_nop 0
	v_add3_u32 v3, v3, v9, s14
	v_add3_u32 v2, v2, v7, s14
	s_nop 0
	s_nop 0
	v_mov_b32_e32 v5, v206
	v_mov_b32_e32 v4, v207
	v_bfe_u32 v7, v8, 16, 1
	v_cvt_pk_bf16_f32 v208, v12, v62
	v_lshrrev_b32_e32 v3, 16, v3
	v_add3_u32 v7, v8, v7, s14
	s_nop 0
	v_bfe_u32 v9, v6, 16, 1
	s_nop 0
	v_and_or_b32 v3, v15, s15, v3
	v_cvt_pk_bf16_f32 v209, v115, v116
	v_add3_u32 v6, v6, v9, s14
	s_nop 0
	s_nop 0
	s_nop 0
	v_lshrrev_b32_e32 v6, 16, v6
	s_nop 0
	s_nop 0
	v_and_or_b32 v9, v7, s15, v6
	v_mov_b32_e32 v8, v208
	v_mov_b32_e32 v7, v209
	v_cvt_pk_bf16_f32 v210, v87, v88
	v_cvt_pk_bf16_f32 v211, v13, v86
	s_nop 0
	s_nop 0
	s_nop 0
	s_nop 0
	s_nop 0
	s_nop 0
	v_mov_b32_e32 v13, v210
	v_mov_b32_e32 v12, v211
	s_nop 0
	s_nop 0
	s_nop 0
	s_nop 0
	v_cvt_pk_bf16_f32 v212, v18, v14
	v_cvt_pk_bf16_f32 v213, v16, v20
	s_nop 0
	s_nop 0
	s_nop 0
	s_nop 0
	v_mov_b32_e32 v15, v212
	v_mov_b32_e32 v14, v213
	v_bfe_u32 v29, v21, 16, 1
	v_add3_u32 v29, v21, v29, s14
	v_bfe_u32 v21, v46, 16, 1
	v_add3_u32 v21, v46, v21, s14
	v_add_co_u32_e32 v46, vcc, s74, v78
	ds_read_b64 v[74:75], v0
	ds_read_b64 v[76:77], v0 offset:32
	s_nop 0
	v_addc_co_u32_e32 v47, vcc, 0, v79, vcc
	global_load_dwordx2 v[46:47], v[46:47], off offset:1024
	ds_read_b64 v[80:81], v0 offset:128
	ds_read_b64 v[82:83], v0 offset:160
	v_lshrrev_b32_e32 v2, 16, v2
	v_and_or_b32 v2, v17, s15, v2
	s_nop 0
	v_cvt_pk_bf16_f32 v214, v84, v85
	s_waitcnt lgkmcnt(2)
	v_mfma_f32_16x16x32_bf16 v[74:77], v[74:77], v[2:5], 0
	s_nop 0
	s_nop 0
	s_nop 0
	v_mov_b32_e32 v6, v214
	s_nop 0
	v_cvt_pk_bf16_f32 v215, v11, v59
	s_waitcnt lgkmcnt(0)
	v_mfma_f32_16x16x32_bf16 v[60:63], v[80:83], v[6:9], v[74:77]
	v_cvt_pk_bf16_f32 v216, v10, v58
	s_nop 0
	s_nop 0
	ds_read_b64 v[74:75], v0 offset:256
	ds_read_b64 v[76:77], v0 offset:288
	s_nop 0
	s_nop 0
	s_nop 0
	v_mov_b32_e32 v11, v215
	v_mov_b32_e32 v10, v216
	s_nop 0
	v_cvt_pk_bf16_f32 v217, v69, v73
	s_waitcnt lgkmcnt(0)
	v_mfma_f32_16x16x32_bf16 v[58:61], v[74:77], v[10:13], v[60:63]
	v_cvt_pk_bf16_f32 v218, v68, v72
	s_nop 0
	s_nop 0
	ds_read_b64 v[62:63], v0 offset:384
	ds_read_b64 v[64:65], v0 offset:416
	s_nop 0
	s_nop 0
	s_nop 0
	s_nop 0
	s_nop 0
	v_mov_b32_e32 v17, v217
	v_mov_b32_e32 v16, v218
	v_bfe_u32 v35, v19, 16, 1
	s_nop 0
	s_waitcnt lgkmcnt(0)
	v_mfma_f32_16x16x32_bf16 v[58:61], v[62:65], v[14:17], v[58:61]
	ds_read_b64 v[62:63], v0 offset:512
	ds_read_b64 v[64:65], v0 offset:544
	s_nop 0
	v_bfe_u32 v18, v56, 16, 1
	v_cvt_pk_bf16_f32 v219, v66, v70
	v_cvt_pk_bf16_f32 v220, v89, v91
	s_nop 0
	s_nop 0
	v_add3_u32 v19, v19, v35, s14
	v_add3_u32 v18, v56, v18, s14
	s_nop 0
	s_nop 0
	v_lshrrev_b32_e32 v21, 16, v21
	v_lshrrev_b32_e32 v35, 16, v19
	s_nop 0
	s_nop 0
	v_and_or_b32 v21, v18, s15, v21
	v_mov_b32_e32 v20, v219
	v_mov_b32_e32 v19, v220
	v_and_or_b32 v18, v29, s15, v35
	v_cvt_pk_bf16_f32 v221, v92, v93
	s_nop 0
	s_waitcnt lgkmcnt(0)
; __device__ __forceinline__ unsigned pk2(float lo, float hi) { return f2bf(lo) | (f2bf(hi) << 16); }
; __device__ __forceinline__ float bflo(unsigned u) { return __uint_as_float(u << 16); }
; __device__ __forceinline__ float bfhi(unsigned u) { return __uint_as_float(u & 0xffff0000u); }
; __device__ __forceinline__ float silu_f(float v) { return v / (1.f + __expf(-v)); }
; #define MFMA16(a, b, c) __builtin_amdgcn_mfma_f32_16x16x32_bf16(a, b, c, 0, 0, 0)
; __device__ __forceinline__ void na2_task(const Params& p_, int l, int task, unsigned char* lds) {
;     ...
; #pragma unroll
;     for (int dt = 0; dt < 4; ++dt) { f32x4 o = {0.f, 0.f, 0.f, 0.f};
; #pragma unroll
;         for (int t = 0; t < 8; ++t) { const int k0 = 2 * t, k1 = 2 * t + 1, a0 = k0 / 2, c0 = k0 % 2, a1 = k1 / 2, c1 = k1 % 2;
;             const u32x2 vlo = *(const u32x2*)(VTh + (16 * dt + fr) * 520 + a0 * 64 + kst + 16 * c0 + 4 * fq), vhi = *(const u32x2*)(VTh + (16 * dt + fr) * 520 + a1 * 64 + kst + 16 * c1 + 4 * fq);
;             o = MFMA16(mk8(vlo.x, vlo.y, vhi.x, vhi.y), mk8(pp[k0][0], pp[k0][1], pp[k1][0], pp[k1][1]), o); }
;         const u32x2 gz = *(const u32x2*)(Z + qtok * DIN + 5 * DG + h * 64 + 16 * dt + 4 * fq); u32x2 ov;
;         ov.x = pk2(o[0] * inv * silu_f(bflo(gz.x)), o[1] * inv * silu_f(bfhi(gz.x))); ov.y = pk2(o[2] * inv * silu_f(bflo(gz.y)), o[3] * inv * silu_f(bfhi(gz.y)));
;         *(u32x2*)(CAT + qtok * DM + 512 + h * 64 + 16 * dt + 4 * fq) = ov; }
	v_mfma_f32_16x16x32_bf16 v[56:59], v[62:65], v[18:21], v[58:61]
	v_bfe_u32 v35, v25, 16, 1
	v_bfe_u32 v37, v24, 16, 1
	v_add3_u32 v37, v24, v37, s14
	ds_read_b64 v[60:61], v0 offset:640
	ds_read_b64 v[62:63], v0 offset:672
	v_add3_u32 v35, v25, v35, s14
	s_nop 0
	s_nop 0
	v_bfe_u32 v27, v22, 16, 1
	v_bfe_u32 v29, v23, 16, 1
	v_cvt_pk_bf16_f32 v222, v67, v71
	s_nop 0
	v_add3_u32 v23, v23, v29, s14
	v_add3_u32 v22, v22, v27, s14
	v_lshrrev_b32_e32 v22, 16, v22
	v_lshrrev_b32_e32 v23, 16, v23
	s_nop 0
	s_nop 0
	v_mov_b32_e32 v25, v221
	v_mov_b32_e32 v24, v222
	v_and_or_b32 v23, v35, s15, v23
	v_and_or_b32 v22, v37, s15, v22
	s_nop 0
	s_nop 0
	s_waitcnt lgkmcnt(0)
	v_mfma_f32_16x16x32_bf16 v[56:59], v[60:63], v[22:25], v[56:59]
	ds_read_b64 v[60:61], v0 offset:768
	ds_read_b64 v[62:63], v0 offset:800
	s_nop 0
	s_nop 0
	v_cvt_pk_bf16_f32 v223, v30, v26
	v_cvt_pk_bf16_f32 v226, v28, v32
	s_nop 0
	s_nop 0
	v_cvt_pk_bf16_f32 v224, v49, v53
	v_cvt_pk_bf16_f32 v225, v48, v52
	s_nop 0
	s_nop 0
	s_nop 0
	s_nop 0
	s_nop 0
	s_nop 0
	s_nop 0
	s_nop 0
	s_nop 0
	s_nop 0
	v_mov_b32_e32 v27, v223
	v_mov_b32_e32 v29, v224
	v_mov_b32_e32 v28, v225
	v_mov_b32_e32 v26, v226
	v_bfe_u32 v30, v36, 16, 1
	v_bfe_u32 v37, v33, 16, 1
	s_waitcnt lgkmcnt(0)
	v_mfma_f32_16x16x32_bf16 v[56:59], v[60:63], v[26:29], v[56:59]
	ds_read_b64 v[60:61], v0 offset:896
	ds_read_b64 v[62:63], v0 offset:928
	v_add3_u32 v30, v36, v30, s14
	v_add3_u32 v36, v33, v37, s14
	v_bfe_u32 v33, v34, 16, 1
	v_bfe_u32 v37, v31, 16, 1
	s_nop 0
	s_nop 0
	v_cvt_pk_bf16_f32 v227, v50, v54
	v_cvt_pk_bf16_f32 v228, v94, v95
	v_add3_u32 v33, v34, v33, s14
	s_nop 0
	s_nop 0
	v_add3_u32 v31, v31, v37, s14
	s_nop 0
	s_nop 0
	v_lshrrev_b32_e32 v33, 16, v33
	v_lshrrev_b32_e32 v37, 16, v31
	s_nop 0
	s_nop 0
	v_and_or_b32 v33, v30, s15, v33
	v_mov_b32_e32 v32, v227
	v_mov_b32_e32 v31, v228
	v_and_or_b32 v30, v36, s15, v37
	s_waitcnt vmcnt(0)
	v_lshlrev_b32_e32 v41, 16, v47
	v_lshl_add_u64 v[44:45], v[78:79], 0, s[12:13]
	s_waitcnt lgkmcnt(0)
	v_mfma_f32_16x16x32_bf16 v[34:37], v[60:63], v[30:33], v[56:59]
	global_load_dwordx2 v[48:49], v[44:45], off offset:32
	global_load_dwordx2 v[50:51], v[44:45], off offset:64
	s_nop 0
	global_load_dwordx2 v[44:45], v[44:45], off offset:96
	v_lshlrev_b32_e32 v56, 16, v46
	v_mul_f32_e32 v52, 0xbfb8aa3b, v56
	v_and_b32_e32 v57, 0xffff0000, v47
	v_mul_f32_e32 v47, 0xbfb8aa3b, v41
	v_exp_f32_e32 v52, v52
	v_exp_f32_e32 v53, v47
	s_mov_b64 s[12:13], 0x12d20400
	v_lshl_add_u64 v[38:39], v[42:43], 0, s[12:13]
	v_mov_b32_e32 v54, v34
	v_pk_add_f32 v[52:53], v[52:53], 1.0 op_sel_hi:[1,0]
	v_mov_b32_e32 v55, v36
	v_div_scale_f32 v47, s[12:13], v53, v53, v41
	v_rcp_f32_e32 v59, v47
	v_and_b32_e32 v58, 0xffff0000, v46
	v_pk_mul_f32 v[54:55], v[40:41], v[54:55] op_sel_hi:[0,1]
	v_mul_f32_e32 v46, 0xbfb8aa3b, v58
	v_fma_f32 v34, -v47, v59, 1.0
	v_fmac_f32_e32 v59, v34, v59
	v_div_scale_f32 v34, vcc, v41, v53, v41
	v_mul_f32_e32 v36, v34, v59
	v_fma_f32 v60, -v47, v36, v34
	v_fmac_f32_e32 v36, v60, v59
	v_fma_f32 v34, -v47, v36, v34
	v_div_scale_f32 v47, s[12:13], v52, v52, v56
	v_rcp_f32_e32 v60, v47
	v_div_fmas_f32 v34, v34, v59, v36
	v_div_fixup_f32 v53, v34, v53, v41
	v_exp_f32_e32 v46, v46
	v_fma_f32 v34, -v47, v60, 1.0
	v_fmac_f32_e32 v60, v34, v60
	v_div_scale_f32 v34, vcc, v56, v52, v56
	v_mul_f32_e32 v36, v34, v60
	v_fma_f32 v41, -v47, v36, v34
	v_fmac_f32_e32 v36, v41, v60
	v_mul_f32_e32 v41, 0xbfb8aa3b, v57
	v_fma_f32 v34, -v47, v36, v34
	v_exp_f32_e32 v47, v41
	v_div_fmas_f32 v34, v34, v60, v36
	v_div_fixup_f32 v52, v34, v52, v56
	v_mov_b32_e32 v36, v35
	v_pk_add_f32 v[46:47], v[46:47], 1.0 op_sel_hi:[1,0]
	v_pk_mul_f32 v[64:65], v[54:55], v[52:53]
	v_div_scale_f32 v34, s[12:13], v47, v47, v57
	v_rcp_f32_e32 v41, v34
	v_div_scale_f32 v52, s[12:13], v46, v46, v58
	v_rcp_f32_e32 v56, v52
	v_fma_f32 v35, -v34, v41, 1.0
	v_pk_mul_f32 v[60:61], v[40:41], v[36:37] op_sel_hi:[0,1]
	v_fmac_f32_e32 v41, v35, v41
	v_div_scale_f32 v35, vcc, v57, v47, v57
	v_mul_f32_e32 v36, v35, v41
	v_fma_f32 v37, -v34, v36, v35
	v_fmac_f32_e32 v36, v37, v41
	v_fma_f32 v34, -v34, v36, v35
	v_div_fmas_f32 v34, v34, v41, v36
	v_div_fixup_f32 v47, v34, v47, v57
	v_fma_f32 v34, -v52, v56, 1.0
	v_add_u32_e32 v66, 0x4000, v0
	v_fmac_f32_e32 v56, v34, v56
	v_div_scale_f32 v41, vcc, v58, v46, v58
	ds_read_b64 v[34:35], v66 offset:256
	ds_read_b64 v[36:37], v66 offset:288
	v_mul_f32_e32 v57, v41, v56
	v_fma_f32 v53, -v52, v57, v41
	v_fmac_f32_e32 v57, v53, v56
	v_fma_f32 v41, -v52, v57, v41
	ds_read_b64 v[52:53], v66 offset:384
	ds_read_b64 v[54:55], v66 offset:416
	v_div_fmas_f32 v41, v41, v56, v57
	v_div_fixup_f32 v46, v41, v46, v58
	ds_read_b64 v[56:57], v66 offset:512
	ds_read_b64 v[58:59], v66 offset:544
	s_waitcnt lgkmcnt(4)
	v_mfma_f32_16x16x32_bf16 v[34:37], v[34:37], v[2:5], 0
	v_mul_f32_e64 v46, v60, v46
	v_mul_f32_e64 v47, v61, v47
	ds_read_b64 v[60:61], v66 offset:640
	ds_read_b64 v[62:63], v66 offset:672
	v_and_b32_sdwa v41, v65, v179 dst_sel:DWORD dst_unused:UNUSED_PAD src0_sel:WORD_1 src1_sel:DWORD
	s_waitcnt lgkmcnt(4)
	v_mfma_f32_16x16x32_bf16 v[34:37], v[52:55], v[6:9], v[34:37]
	v_and_b32_sdwa v52, v64, v179 dst_sel:DWORD dst_unused:UNUSED_PAD src0_sel:WORD_1 src1_sel:DWORD
	v_add3_u32 v64, v64, v52, s14
	ds_read_b64 v[52:53], v66 offset:768
	ds_read_b64 v[54:55], v66 offset:800
	s_waitcnt lgkmcnt(4)
	v_mfma_f32_16x16x32_bf16 v[34:37], v[56:59], v[10:13], v[34:37]
	ds_read_b64 v[56:57], v66 offset:896
	ds_read_b64 v[58:59], v66 offset:928
	v_add3_u32 v41, v65, v41, s14
	v_and_b32_sdwa v65, v47, v179 dst_sel:DWORD dst_unused:UNUSED_PAD src0_sel:WORD_1 src1_sel:DWORD
	s_waitcnt lgkmcnt(4)
; __device__ __forceinline__ unsigned pk2(float lo, float hi) { return f2bf(lo) | (f2bf(hi) << 16); }
; __device__ __forceinline__ float bflo(unsigned u) { return __uint_as_float(u << 16); }
; __device__ __forceinline__ float bfhi(unsigned u) { return __uint_as_float(u & 0xffff0000u); }
; __device__ __forceinline__ float silu_f(float v) { return v / (1.f + __expf(-v)); }
; #define MFMA16(a, b, c) __builtin_amdgcn_mfma_f32_16x16x32_bf16(a, b, c, 0, 0, 0)
; __device__ __forceinline__ void na2_task(const Params& p_, int l, int task, unsigned char* lds) {
;     ...
; #pragma unroll
;     for (int dt = 0; dt < 4; ++dt) { f32x4 o = {0.f, 0.f, 0.f, 0.f};
; #pragma unroll
;         for (int t = 0; t < 8; ++t) { const int k0 = 2 * t, k1 = 2 * t + 1, a0 = k0 / 2, c0 = k0 % 2, a1 = k1 / 2, c1 = k1 % 2;
;             const u32x2 vlo = *(const u32x2*)(VTh + (16 * dt + fr) * 520 + a0 * 64 + kst + 16 * c0 + 4 * fq), vhi = *(const u32x2*)(VTh + (16 * dt + fr) * 520 + a1 * 64 + kst + 16 * c1 + 4 * fq);
;             o = MFMA16(mk8(vlo.x, vlo.y, vhi.x, vhi.y), mk8(pp[k0][0], pp[k0][1], pp[k1][0], pp[k1][1]), o); }
;         const u32x2 gz = *(const u32x2*)(Z + qtok * DIN + 5 * DG + h * 64 + 16 * dt + 4 * fq); u32x2 ov;
;         ov.x = pk2(o[0] * inv * silu_f(bflo(gz.x)), o[1] * inv * silu_f(bfhi(gz.x))); ov.y = pk2(o[2] * inv * silu_f(bflo(gz.y)), o[3] * inv * silu_f(bfhi(gz.y)));
;         *(u32x2*)(CAT + qtok * DM + 512 + h * 64 + 16 * dt + 4 * fq) = ov; }
	v_mfma_f32_16x16x32_bf16 v[34:37], v[60:63], v[14:17], v[34:37]
	ds_read_b64 v[60:61], v66 offset:1024
	ds_read_b64 v[62:63], v66 offset:1056
	v_and_b32_sdwa v67, v46, v179 dst_sel:DWORD dst_unused:UNUSED_PAD src0_sel:WORD_1 src1_sel:DWORD
	v_add3_u32 v47, v47, v65, s14
	s_waitcnt lgkmcnt(4)
	v_mfma_f32_16x16x32_bf16 v[34:37], v[52:55], v[18:21], v[34:37]
	ds_read_b64 v[52:53], v66 offset:1152
	ds_read_b64 v[54:55], v66 offset:1184
	v_add3_u32 v46, v46, v67, s14
	v_and_b32_e32 v47, 0xffff0000, v47
	s_waitcnt lgkmcnt(4)
	v_mfma_f32_16x16x32_bf16 v[34:37], v[56:59], v[22:25], v[34:37]
	v_and_b32_e32 v46, 0xffff0000, v46
	v_add_co_u32_e32 v42, vcc, s9, v42
	s_waitcnt lgkmcnt(2)
	v_mfma_f32_16x16x32_bf16 v[34:37], v[60:63], v[26:29], v[34:37]
	v_or_b32_sdwa v47, v47, v41 dst_sel:DWORD dst_unused:UNUSED_PAD src0_sel:DWORD src1_sel:WORD_1
	v_or_b32_sdwa v46, v46, v64 dst_sel:DWORD dst_unused:UNUSED_PAD src0_sel:DWORD src1_sel:WORD_1
	v_addc_co_u32_e32 v43, vcc, 0, v43, vcc
	s_waitcnt lgkmcnt(0)
	v_mfma_f32_16x16x32_bf16 v[34:37], v[52:55], v[30:33], v[34:37]
	s_waitcnt vmcnt(2)
	v_lshlrev_b32_e32 v41, 16, v49
	v_lshlrev_b32_e32 v52, 16, v48
	global_store_dwordx2 v[42:43], v[46:47], off offset:1024
	v_mul_f32_e32 v42, 0xbfb8aa3b, v52
	v_mul_f32_e32 v43, 0xbfb8aa3b, v41
	v_exp_f32_e32 v42, v42
	v_exp_f32_e32 v43, v43
	v_and_b32_e32 v58, 0xffff0000, v48
	v_mov_b32_e32 v48, v34
	v_and_b32_e32 v53, 0xffff0000, v49
	v_pk_add_f32 v[42:43], v[42:43], 1.0 op_sel_hi:[1,0]
	v_mov_b32_e32 v49, v36
	v_div_scale_f32 v47, s[12:13], v43, v43, v41
	v_rcp_f32_e32 v54, v47
	v_pk_mul_f32 v[48:49], v[40:41], v[48:49] op_sel_hi:[0,1]
	v_mul_f32_e32 v46, 0xbfb8aa3b, v58
	v_exp_f32_e32 v46, v46
	v_fma_f32 v34, -v47, v54, 1.0
	v_fmac_f32_e32 v54, v34, v54
	v_div_scale_f32 v34, vcc, v41, v43, v41
	v_mul_f32_e32 v36, v34, v54
	v_fma_f32 v55, -v47, v36, v34
	v_fmac_f32_e32 v36, v55, v54
	v_fma_f32 v34, -v47, v36, v34
	v_div_scale_f32 v47, s[12:13], v42, v42, v52
	v_rcp_f32_e32 v55, v47
	v_div_fmas_f32 v34, v34, v54, v36
	v_div_fixup_f32 v43, v34, v43, v41
	v_add_u32_e32 v64, 0x8000, v0
	v_fma_f32 v34, -v47, v55, 1.0
	v_fmac_f32_e32 v55, v34, v55
	v_div_scale_f32 v34, vcc, v52, v42, v52
	v_mul_f32_e32 v36, v34, v55
	v_fma_f32 v41, -v47, v36, v34
	v_fmac_f32_e32 v36, v41, v55
	v_mul_f32_e32 v41, 0xbfb8aa3b, v53
	v_fma_f32 v34, -v47, v36, v34
	v_exp_f32_e32 v47, v41
	v_div_fmas_f32 v34, v34, v55, v36
	v_div_fixup_f32 v42, v34, v42, v52
	v_mov_b32_e32 v36, v35
	v_pk_add_f32 v[56:57], v[46:47], 1.0 op_sel_hi:[1,0]
	v_pk_mul_f32 v[42:43], v[48:49], v[42:43]
	v_div_scale_f32 v34, s[12:13], v57, v57, v53
	v_rcp_f32_e32 v41, v34
	v_div_scale_f32 v52, s[12:13], v56, v56, v58
	v_rcp_f32_e32 v59, v52
	v_fma_f32 v35, -v34, v41, 1.0
	v_pk_mul_f32 v[60:61], v[40:41], v[36:37] op_sel_hi:[0,1]
	v_fmac_f32_e32 v41, v35, v41
	v_div_scale_f32 v35, vcc, v53, v57, v53
	v_mul_f32_e32 v36, v35, v41
	v_fma_f32 v37, -v34, v36, v35
	v_fmac_f32_e32 v36, v37, v41
	v_fma_f32 v34, -v34, v36, v35
	v_div_fmas_f32 v34, v34, v41, v36
	v_div_fixup_f32 v63, v34, v57, v53
	ds_read_b64 v[34:35], v64 offset:512
	ds_read_b64 v[36:37], v64 offset:544
	v_fma_f32 v41, -v52, v59, 1.0
	v_fmac_f32_e32 v59, v41, v59
	v_div_scale_f32 v41, vcc, v58, v56, v58
	ds_read_b64 v[46:47], v64 offset:640
	ds_read_b64 v[48:49], v64 offset:672
	v_mul_f32_e32 v57, v41, v59
	v_fma_f32 v53, -v52, v57, v41
	v_fmac_f32_e32 v57, v53, v59
	v_fma_f32 v41, -v52, v57, v41
	ds_read_b64 v[52:53], v64 offset:768
	ds_read_b64 v[54:55], v64 offset:800
	s_waitcnt lgkmcnt(4)
	v_mfma_f32_16x16x32_bf16 v[34:37], v[34:37], v[2:5], 0
	v_div_fmas_f32 v41, v41, v59, v57
	v_div_fixup_f32 v62, v41, v56, v58
	ds_read_b64 v[56:57], v64 offset:896
	ds_read_b64 v[58:59], v64 offset:928
	s_waitcnt lgkmcnt(4)
	v_mfma_f32_16x16x32_bf16 v[34:37], v[46:49], v[6:9], v[34:37]
	ds_read_b64 v[46:47], v64 offset:1024
	ds_read_b64 v[48:49], v64 offset:1056
	v_pk_mul_f32 v[60:61], v[60:61], v[62:63]
	v_and_b32_sdwa v41, v43, v179 dst_sel:DWORD dst_unused:UNUSED_PAD src0_sel:WORD_1 src1_sel:DWORD
	s_waitcnt lgkmcnt(4)
	v_mfma_f32_16x16x32_bf16 v[34:37], v[52:55], v[10:13], v[34:37]
	v_and_b32_sdwa v52, v42, v179 dst_sel:DWORD dst_unused:UNUSED_PAD src0_sel:WORD_1 src1_sel:DWORD
	v_add3_u32 v42, v42, v52, s14
	ds_read_b64 v[52:53], v64 offset:1152
	ds_read_b64 v[54:55], v64 offset:1184
	s_waitcnt lgkmcnt(4)
	v_mfma_f32_16x16x32_bf16 v[34:37], v[56:59], v[14:17], v[34:37]
	ds_read_b64 v[56:57], v64 offset:1280
	ds_read_b64 v[58:59], v64 offset:1312
	v_add3_u32 v41, v43, v41, s14
	v_and_b32_sdwa v43, v61, v179 dst_sel:DWORD dst_unused:UNUSED_PAD src0_sel:WORD_1 src1_sel:DWORD
	s_waitcnt lgkmcnt(4)
	v_mfma_f32_16x16x32_bf16 v[34:37], v[46:49], v[18:21], v[34:37]
	v_and_b32_sdwa v62, v60, v179 dst_sel:DWORD dst_unused:UNUSED_PAD src0_sel:WORD_1 src1_sel:DWORD
	v_add3_u32 v43, v61, v43, s14
	ds_read_b64 v[46:47], v64 offset:1408
	ds_read_b64 v[48:49], v64 offset:1440
	s_waitcnt lgkmcnt(4)
	v_mfma_f32_16x16x32_bf16 v[34:37], v[52:55], v[22:25], v[34:37]
	v_add3_u32 v52, v60, v62, s14
	v_and_b32_e32 v43, 0xffff0000, v43
	v_and_b32_e32 v52, 0xffff0000, v52
	v_or_b32_sdwa v43, v43, v41 dst_sel:DWORD dst_unused:UNUSED_PAD src0_sel:DWORD src1_sel:WORD_1
	v_or_b32_sdwa v42, v52, v42 dst_sel:DWORD dst_unused:UNUSED_PAD src0_sel:DWORD src1_sel:WORD_1
	s_waitcnt vmcnt(2)
	v_lshlrev_b32_e32 v41, 16, v51
	v_lshlrev_b32_e32 v52, 16, v50
	global_store_dwordx2 v[38:39], v[42:43], off offset:32
	v_mul_f32_e32 v42, 0xbfb8aa3b, v52
	v_mul_f32_e32 v43, 0xbfb8aa3b, v41
	v_exp_f32_e32 v42, v42
	v_exp_f32_e32 v43, v43
	s_waitcnt lgkmcnt(2)
; __device__ __forceinline__ unsigned pk2(float lo, float hi) { return f2bf(lo) | (f2bf(hi) << 16); }
; __device__ __forceinline__ float bflo(unsigned u) { return __uint_as_float(u << 16); }
; __device__ __forceinline__ float bfhi(unsigned u) { return __uint_as_float(u & 0xffff0000u); }
; __device__ __forceinline__ float silu_f(float v) { return v / (1.f + __expf(-v)); }
; #define MFMA16(a, b, c) __builtin_amdgcn_mfma_f32_16x16x32_bf16(a, b, c, 0, 0, 0)
; __device__ __forceinline__ void na2_task(const Params& p_, int l, int task, unsigned char* lds) {
;     ...
; #pragma unroll
;     for (int dt = 0; dt < 4; ++dt) { f32x4 o = {0.f, 0.f, 0.f, 0.f};
; #pragma unroll
;         for (int t = 0; t < 8; ++t) { const int k0 = 2 * t, k1 = 2 * t + 1, a0 = k0 / 2, c0 = k0 % 2, a1 = k1 / 2, c1 = k1 % 2;
;             const u32x2 vlo = *(const u32x2*)(VTh + (16 * dt + fr) * 520 + a0 * 64 + kst + 16 * c0 + 4 * fq), vhi = *(const u32x2*)(VTh + (16 * dt + fr) * 520 + a1 * 64 + kst + 16 * c1 + 4 * fq);
;             o = MFMA16(mk8(vlo.x, vlo.y, vhi.x, vhi.y), mk8(pp[k0][0], pp[k0][1], pp[k1][0], pp[k1][1]), o); }
;         const u32x2 gz = *(const u32x2*)(Z + qtok * DIN + 5 * DG + h * 64 + 16 * dt + 4 * fq); u32x2 ov;
;         ov.x = pk2(o[0] * inv * silu_f(bflo(gz.x)), o[1] * inv * silu_f(bfhi(gz.x))); ov.y = pk2(o[2] * inv * silu_f(bflo(gz.y)), o[3] * inv * silu_f(bfhi(gz.y)));
;         *(u32x2*)(CAT + qtok * DM + 512 + h * 64 + 16 * dt + 4 * fq) = ov; }
	v_mfma_f32_16x16x32_bf16 v[34:37], v[56:59], v[26:29], v[34:37]
	v_and_b32_e32 v56, 0xffff0000, v50
	v_and_b32_e32 v53, 0xffff0000, v51
	v_pk_add_f32 v[42:43], v[42:43], 1.0 op_sel_hi:[1,0]
	s_waitcnt lgkmcnt(0)
	v_mfma_f32_16x16x32_bf16 v[34:37], v[46:49], v[30:33], v[34:37]
	v_div_scale_f32 v47, s[12:13], v43, v43, v41
	v_rcp_f32_e32 v50, v47
	v_mul_f32_e32 v46, 0xbfb8aa3b, v56
	v_exp_f32_e32 v46, v46
	s_nop 3
	v_mov_b32_e32 v48, v34
	v_fma_f32 v34, -v47, v50, 1.0
	v_fmac_f32_e32 v50, v34, v50
	v_div_scale_f32 v34, vcc, v41, v43, v41
	v_mov_b32_e32 v49, v36
	v_mul_f32_e32 v36, v34, v50
	v_fma_f32 v51, -v47, v36, v34
	v_fmac_f32_e32 v36, v51, v50
	v_fma_f32 v34, -v47, v36, v34
	v_div_scale_f32 v47, s[12:13], v42, v42, v52
	v_rcp_f32_e32 v51, v47
	v_div_fmas_f32 v34, v34, v50, v36
	v_div_fixup_f32 v43, v34, v43, v41
	v_pk_mul_f32 v[48:49], v[40:41], v[48:49] op_sel_hi:[0,1]
	v_fma_f32 v34, -v47, v51, 1.0
	v_fmac_f32_e32 v51, v34, v51
	v_div_scale_f32 v34, vcc, v52, v42, v52
	v_mul_f32_e32 v36, v34, v51
	v_fma_f32 v41, -v47, v36, v34
	v_fmac_f32_e32 v36, v41, v51
	v_mul_f32_e32 v41, 0xbfb8aa3b, v53
	v_fma_f32 v34, -v47, v36, v34
	v_exp_f32_e32 v47, v41
	v_div_fmas_f32 v34, v34, v51, v36
	v_div_fixup_f32 v42, v34, v42, v52
	v_mov_b32_e32 v36, v35
	v_pk_add_f32 v[50:51], v[46:47], 1.0 op_sel_hi:[1,0]
	v_add_u32_e32 v0, 0xc000, v0
	v_div_scale_f32 v34, s[12:13], v51, v51, v53
	v_rcp_f32_e32 v41, v34
	v_div_scale_f32 v52, s[12:13], v50, v50, v56
	v_rcp_f32_e32 v58, v52
	v_fma_f32 v35, -v34, v41, 1.0
	v_pk_mul_f32 v[54:55], v[40:41], v[36:37] op_sel_hi:[0,1]
	v_fmac_f32_e32 v41, v35, v41
	v_div_scale_f32 v35, vcc, v53, v51, v53
	v_mul_f32_e32 v36, v35, v41
	v_fma_f32 v37, -v34, v36, v35
	v_fmac_f32_e32 v36, v37, v41
	v_fma_f32 v34, -v34, v36, v35
	v_div_fmas_f32 v34, v34, v41, v36
	v_div_fixup_f32 v57, v34, v51, v53
	ds_read_b64 v[34:35], v0 offset:768
	ds_read_b64 v[36:37], v0 offset:800
	v_pk_mul_f32 v[42:43], v[48:49], v[42:43]
	ds_read_b64 v[46:47], v0 offset:896
	ds_read_b64 v[48:49], v0 offset:928
	v_fma_f32 v41, -v52, v58, 1.0
	v_fmac_f32_e32 v58, v41, v58
	v_div_scale_f32 v41, vcc, v56, v50, v56
	v_mul_f32_e32 v51, v41, v58
	v_fma_f32 v53, -v52, v51, v41
	s_waitcnt lgkmcnt(2)
	v_mfma_f32_16x16x32_bf16 v[2:5], v[34:37], v[2:5], 0
	ds_read_b64 v[34:35], v0 offset:1024
	ds_read_b64 v[36:37], v0 offset:1056
	v_fmac_f32_e32 v51, v53, v58
	v_fma_f32 v41, -v52, v51, v41
	v_div_fmas_f32 v41, v41, v58, v51
	v_div_fixup_f32 v56, v41, v50, v56
	ds_read_b64 v[50:51], v0 offset:1152
	ds_read_b64 v[52:53], v0 offset:1184
	s_waitcnt lgkmcnt(4)
	v_mfma_f32_16x16x32_bf16 v[2:5], v[46:49], v[6:9], v[2:5]
	ds_read_b64 v[6:7], v0 offset:1280
	ds_read_b64 v[8:9], v0 offset:1312
	v_pk_mul_f32 v[46:47], v[54:55], v[56:57]
	v_and_b32_sdwa v41, v43, v179 dst_sel:DWORD dst_unused:UNUSED_PAD src0_sel:WORD_1 src1_sel:DWORD
	s_waitcnt lgkmcnt(4)
	v_mfma_f32_16x16x32_bf16 v[2:5], v[34:37], v[10:13], v[2:5]
	v_and_b32_sdwa v10, v42, v179 dst_sel:DWORD dst_unused:UNUSED_PAD src0_sel:WORD_1 src1_sel:DWORD
	v_add3_u32 v34, v42, v10, s14
	ds_read_b64 v[10:11], v0 offset:1408
	ds_read_b64 v[12:13], v0 offset:1440
	s_waitcnt lgkmcnt(4)
	v_mfma_f32_16x16x32_bf16 v[2:5], v[50:53], v[14:17], v[2:5]
	ds_read_b64 v[14:15], v0 offset:1536
	ds_read_b64 v[16:17], v0 offset:1568
	v_and_b32_sdwa v36, v47, v179 dst_sel:DWORD dst_unused:UNUSED_PAD src0_sel:WORD_1 src1_sel:DWORD
	v_add3_u32 v35, v43, v41, s14
	s_waitcnt lgkmcnt(4)
	v_mfma_f32_16x16x32_bf16 v[2:5], v[6:9], v[18:21], v[2:5]
	ds_read_b64 v[6:7], v0 offset:1664
	ds_read_b64 v[8:9], v0 offset:1696
	v_and_b32_sdwa v18, v46, v179 dst_sel:DWORD dst_unused:UNUSED_PAD src0_sel:WORD_1 src1_sel:DWORD
	v_add3_u32 v19, v47, v36, s14
	s_waitcnt lgkmcnt(4)
; __device__ __forceinline__ unsigned pk2(float lo, float hi) { return f2bf(lo) | (f2bf(hi) << 16); }
; __device__ __forceinline__ float bflo(unsigned u) { return __uint_as_float(u << 16); }
; __device__ __forceinline__ float bfhi(unsigned u) { return __uint_as_float(u & 0xffff0000u); }
; __device__ __forceinline__ float silu_f(float v) { return v / (1.f + __expf(-v)); }
; #define MFMA16(a, b, c) __builtin_amdgcn_mfma_f32_16x16x32_bf16(a, b, c, 0, 0, 0)
; __device__ __forceinline__ void na2_task(const Params& p_, int l, int task, unsigned char* lds) {
;     ...
; #pragma unroll
;     for (int dt = 0; dt < 4; ++dt) { f32x4 o = {0.f, 0.f, 0.f, 0.f};
; #pragma unroll
;         for (int t = 0; t < 8; ++t) { const int k0 = 2 * t, k1 = 2 * t + 1, a0 = k0 / 2, c0 = k0 % 2, a1 = k1 / 2, c1 = k1 % 2;
;             const u32x2 vlo = *(const u32x2*)(VTh + (16 * dt + fr) * 520 + a0 * 64 + kst + 16 * c0 + 4 * fq), vhi = *(const u32x2*)(VTh + (16 * dt + fr) * 520 + a1 * 64 + kst + 16 * c1 + 4 * fq);
;             o = MFMA16(mk8(vlo.x, vlo.y, vhi.x, vhi.y), mk8(pp[k0][0], pp[k0][1], pp[k1][0], pp[k1][1]), o); }
;         const u32x2 gz = *(const u32x2*)(Z + qtok * DIN + 5 * DG + h * 64 + 16 * dt + 4 * fq); u32x2 ov;
;         ov.x = pk2(o[0] * inv * silu_f(bflo(gz.x)), o[1] * inv * silu_f(bfhi(gz.x))); ov.y = pk2(o[2] * inv * silu_f(bflo(gz.y)), o[3] * inv * silu_f(bfhi(gz.y)));
;         *(u32x2*)(CAT + qtok * DM + 512 + h * 64 + 16 * dt + 4 * fq) = ov; }
;     __syncthreads();
; __device__ __forceinline__ void ph_mixA(const Params& p, int l, unsigned char* lds) {
;     ...
;         for (int i = 0; i < nloc; ++i) { const int rq = (slot < 16) ? slot : 16 + i * 16 + (slot - 16);
;             na2_task(p, l, (xcd >> 2) * 256 + rq * 4 + (xcd & 3), lds); }
	v_mfma_f32_16x16x32_bf16 v[2:5], v[10:13], v[22:25], v[2:5]
	v_add3_u32 v0, v46, v18, s14
	v_and_b32_e32 v10, 0xffff0000, v19
	v_and_b32_e32 v0, 0xffff0000, v0
	s_waitcnt lgkmcnt(2)
	v_mfma_f32_16x16x32_bf16 v[2:5], v[14:17], v[26:29], v[2:5]
	v_or_b32_sdwa v11, v10, v35 dst_sel:DWORD dst_unused:UNUSED_PAD src0_sel:DWORD src1_sel:WORD_1
	v_or_b32_sdwa v10, v0, v34 dst_sel:DWORD dst_unused:UNUSED_PAD src0_sel:DWORD src1_sel:WORD_1
	s_waitcnt vmcnt(2)
	v_lshlrev_b32_e32 v0, 16, v45
	v_lshlrev_b32_e32 v12, 16, v44
	s_waitcnt lgkmcnt(0)
	v_mfma_f32_16x16x32_bf16 v[2:5], v[6:9], v[30:33], v[2:5]
	v_mul_f32_e32 v6, 0xbfb8aa3b, v12
	v_mul_f32_e32 v7, 0xbfb8aa3b, v0
	v_exp_f32_e32 v6, v6
	v_exp_f32_e32 v7, v7
	global_store_dwordx2 v[38:39], v[10:11], off offset:64
	s_nop 2
	v_mov_b32_e32 v10, v2
	v_mov_b32_e32 v11, v4
	v_pk_add_f32 v[6:7], v[6:7], 1.0 op_sel_hi:[1,0]
	v_and_b32_e32 v13, 0xffff0000, v45
	v_div_scale_f32 v9, s[12:13], v7, v7, v0
	v_rcp_f32_e32 v15, v9
	v_and_b32_e32 v14, 0xffff0000, v44
	v_mul_f32_e32 v8, 0xbfb8aa3b, v14
	v_exp_f32_e32 v8, v8
	v_fma_f32 v2, -v9, v15, 1.0
	v_fmac_f32_e32 v15, v2, v15
	v_div_scale_f32 v2, vcc, v0, v7, v0
	v_mul_f32_e32 v4, v2, v15
	v_fma_f32 v16, -v9, v4, v2
	v_fmac_f32_e32 v4, v16, v15
	v_fma_f32 v2, -v9, v4, v2
	v_div_scale_f32 v9, s[12:13], v6, v6, v12
	v_rcp_f32_e32 v16, v9
	v_div_fmas_f32 v2, v2, v15, v4
	v_div_fixup_f32 v7, v2, v7, v0
	v_pk_mul_f32 v[10:11], v[40:41], v[10:11] op_sel_hi:[0,1]
	v_fma_f32 v0, -v9, v16, 1.0
	v_fmac_f32_e32 v16, v0, v16
	v_div_scale_f32 v0, vcc, v12, v6, v12
	v_mul_f32_e32 v2, v0, v16
	v_fma_f32 v4, -v9, v2, v0
	v_fmac_f32_e32 v2, v4, v16
	v_mul_f32_e32 v4, 0xbfb8aa3b, v13
	v_fma_f32 v0, -v9, v2, v0
	v_exp_f32_e32 v9, v4
	v_div_fmas_f32 v0, v0, v16, v2
	v_div_fixup_f32 v6, v0, v6, v12
	v_mov_b32_e32 v4, v3
	v_pk_add_f32 v[8:9], v[8:9], 1.0 op_sel_hi:[1,0]
	v_pk_mul_f32 v[2:3], v[40:41], v[4:5] op_sel_hi:[0,1]
	v_div_scale_f32 v0, s[12:13], v9, v9, v13
	v_rcp_f32_e32 v12, v0
	v_pk_mul_f32 v[6:7], v[10:11], v[6:7]
	s_add_i32 s9, s3, 1
	s_cmp_lt_u32 s3, 3
	v_fma_f32 v4, -v0, v12, 1.0
	v_fmac_f32_e32 v12, v4, v12
	v_div_scale_f32 v4, vcc, v13, v9, v13
	v_mul_f32_e32 v5, v4, v12
	v_fma_f32 v10, -v0, v5, v4
	v_fmac_f32_e32 v5, v10, v12
	v_fma_f32 v0, -v0, v5, v4
	v_div_scale_f32 v4, s[12:13], v8, v8, v14
	v_rcp_f32_e32 v10, v4
	v_div_fmas_f32 v0, v0, v12, v5
	v_div_fixup_f32 v5, v0, v9, v13
	s_cselect_b64 s[12:13], -1, 0
	v_fma_f32 v0, -v4, v10, 1.0
	v_fmac_f32_e32 v10, v0, v10
	v_div_scale_f32 v0, vcc, v14, v8, v14
	v_mul_f32_e32 v9, v0, v10
	v_fma_f32 v11, -v4, v9, v0
	v_fmac_f32_e32 v9, v11, v10
	v_fma_f32 v0, -v4, v9, v0
	v_div_fmas_f32 v0, v0, v10, v9
	v_div_fixup_f32 v4, v0, v8, v14
	v_pk_mul_f32 v[2:3], v[2:3], v[4:5]
	v_and_b32_sdwa v4, v6, v179 dst_sel:DWORD dst_unused:UNUSED_PAD src0_sel:WORD_1 src1_sel:DWORD
	v_add3_u32 v4, v6, v4, s14
	v_and_b32_sdwa v5, v3, v179 dst_sel:DWORD dst_unused:UNUSED_PAD src0_sel:WORD_1 src1_sel:DWORD
	v_and_b32_sdwa v6, v2, v179 dst_sel:DWORD dst_unused:UNUSED_PAD src0_sel:WORD_1 src1_sel:DWORD
	v_and_b32_sdwa v0, v7, v179 dst_sel:DWORD dst_unused:UNUSED_PAD src0_sel:WORD_1 src1_sel:DWORD
	v_add3_u32 v3, v3, v5, s14
	v_add3_u32 v2, v2, v6, s14
	v_add3_u32 v0, v7, v0, s14
	v_and_b32_e32 v3, 0xffff0000, v3
	v_and_b32_e32 v2, 0xffff0000, v2
	s_and_b64 s[12:13], s[56:57], s[12:13]
	v_or_b32_sdwa v3, v3, v0 dst_sel:DWORD dst_unused:UNUSED_PAD src0_sel:DWORD src1_sel:WORD_1
	v_or_b32_sdwa v2, v2, v4 dst_sel:DWORD dst_unused:UNUSED_PAD src0_sel:DWORD src1_sel:WORD_1
	s_andn2_b64 vcc, exec, s[12:13]
	s_mov_b32 s3, s9
	global_store_dwordx2 v[38:39], v[2:3], off offset:96
	s_barrier
	s_cbranch_vccnz .LBB0_394
